# gemm8 phases 1,5: MFMA A/B operand swap (transposed accumulators) + bf16 tile staged through LDS + coalesced dwordx4 row stores; plus out-proj counted vmcnt ladder
# speedup vs baseline: 1.0179x; 1.0097x over previous
; #define WAIT_V(n) asm volatile("s_waitcnt vmcnt(" #n ")" ::: "memory")
; #define WAIT_L(n) asm volatile("s_waitcnt lgkmcnt(" #n ")" ::: "memory")
; #define BAR __builtin_amdgcn_s_barrier()
; #define SCHED __builtin_amdgcn_sched_barrier(0)
; template <int EPI>
; __device__ void gemm8_phase(const Params& p, const u16* __restrict__ A, const u16* __restrict__ Bt, const int K, const int nN,
;                             unsigned char* smem, const int rep) {
;     ...
;     for (int t = 0; t < nt - 2; t += 2) {
;       LDB(B0, 0, 0); SCHED; LDA(At, 0, 0); STAGE(SA(1, 1), A, brow + HALF, t + 1);
;       WAIT_L(8); BAR; WAIT_L(0); MMA(0, 0, At, B0); BAR; SCHED;
;       LDB(B1, 0, 1); STAGE(SB(0, 0), Bt, bcol, t + 2);
;       BAR; WAIT_L(0); MMA(0, 1, At, B1); BAR;
;       LDA(At, 0, 1); STAGE(SA(0, 0), A, brow, t + 2);
;       BAR; WAIT_L(0); MMA(1, 0, At, B0); BAR; SCHED;
;       STAGE(SB(0, 1), Bt, bcol + HALF, t + 2);
;       WAIT_V(6); BAR; MMA(1, 1, At, B1); BAR;
.LBB0_202:
	ds_read_b128 v[130:133], v166
	ds_read_b128 v[174:177], v166 offset:1024
	ds_read_b128 v[178:181], v166 offset:2048
	ds_read_b128 v[182:185], v166 offset:3072
	s_add_i32 s45, s7, s44
	v_readfirstlane_b32 s47, v164
	s_or_b32 s46, s45, 0x40080
	s_mov_b32 m0, s47
	v_readfirstlane_b32 s47, v165
	ds_read_b128 v[186:189], v167
	ds_read_b128 v[190:193], v167 offset:1024
	ds_read_b128 v[196:199], v168
	ds_read_b128 v[200:203], v168 offset:1024
	ds_read_b128 v[204:207], v169
	ds_read_b128 v[208:211], v169 offset:1024
	ds_read_b128 v[212:215], v170
	ds_read_b128 v[216:219], v170 offset:1024
	buffer_load_dwordx4 v139, s[12:15], s46 offen lds
	s_mov_b32 m0, s47
	s_nop 0
	buffer_load_dwordx4 v141, s[12:15], s46 offen lds
	s_waitcnt lgkmcnt(8)
	s_barrier
	s_waitcnt lgkmcnt(0)
	s_setprio 1
	s_waitcnt lgkmcnt(7)
	v_mfma_f32_16x16x32_bf16 v[124:127], v[130:133], v[186:189], v[124:127]
	v_mfma_f32_16x16x32_bf16 v[120:123], v[178:181], v[186:189], v[120:123]
	s_waitcnt lgkmcnt(5)
	v_mfma_f32_16x16x32_bf16 v[116:119], v[130:133], v[196:199], v[116:119]
	v_mfma_f32_16x16x32_bf16 v[112:115], v[178:181], v[196:199], v[112:115]
	s_waitcnt lgkmcnt(3)
	v_mfma_f32_16x16x32_bf16 v[108:111], v[130:133], v[204:207], v[108:111]
	v_mfma_f32_16x16x32_bf16 v[104:107], v[178:181], v[204:207], v[104:107]
	s_waitcnt lgkmcnt(1)
	v_mfma_f32_16x16x32_bf16 v[100:103], v[130:133], v[212:215], v[100:103]
	v_mfma_f32_16x16x32_bf16 v[96:99], v[178:181], v[212:215], v[96:99]
	v_mfma_f32_16x16x32_bf16 v[124:127], v[174:177], v[190:193], v[124:127]
	v_mfma_f32_16x16x32_bf16 v[120:123], v[182:185], v[190:193], v[120:123]
	v_mfma_f32_16x16x32_bf16 v[116:119], v[174:177], v[200:203], v[116:119]
	v_mfma_f32_16x16x32_bf16 v[112:115], v[182:185], v[200:203], v[112:115]
	v_mfma_f32_16x16x32_bf16 v[108:111], v[174:177], v[208:211], v[108:111]
	v_mfma_f32_16x16x32_bf16 v[104:107], v[182:185], v[208:211], v[104:107]
	s_waitcnt lgkmcnt(0)
	v_mfma_f32_16x16x32_bf16 v[100:103], v[174:177], v[216:219], v[100:103]
	v_mfma_f32_16x16x32_bf16 v[96:99], v[182:185], v[216:219], v[96:99]
	s_setprio 0
	s_barrier
	s_add_i32 s46, s6, s44
	v_readfirstlane_b32 s48, v152
	s_add_i32 s47, s46, 0x100
	s_mov_b32 m0, s48
	v_readfirstlane_b32 s48, v153
	ds_read_b128 v[220:223], v171
	ds_read_b128 v[224:227], v171 offset:1024
	ds_read_b128 v[228:231], v171 offset:2048
	ds_read_b128 v[232:235], v171 offset:3072
	buffer_load_dwordx4 v139, s[8:11], s47 offen lds
	s_mov_b32 m0, s48
	s_nop 0
	buffer_load_dwordx4 v141, s[8:11], s47 offen lds
	s_barrier
	s_waitcnt lgkmcnt(0)
	s_setprio 1
	s_waitcnt lgkmcnt(3)
	v_mfma_f32_16x16x32_bf16 v[92:95], v[220:223], v[186:189], v[92:95]
	s_waitcnt lgkmcnt(1)
	v_mfma_f32_16x16x32_bf16 v[88:91], v[228:231], v[186:189], v[88:91]
	v_mfma_f32_16x16x32_bf16 v[84:87], v[220:223], v[196:199], v[84:87]
	v_mfma_f32_16x16x32_bf16 v[80:83], v[228:231], v[196:199], v[80:83]
	v_mfma_f32_16x16x32_bf16 v[76:79], v[220:223], v[204:207], v[76:79]
	v_mfma_f32_16x16x32_bf16 v[72:75], v[228:231], v[204:207], v[72:75]
	v_mfma_f32_16x16x32_bf16 v[68:71], v[220:223], v[212:215], v[68:71]
	v_mfma_f32_16x16x32_bf16 v[64:67], v[228:231], v[212:215], v[64:67]
	v_mfma_f32_16x16x32_bf16 v[92:95], v[224:227], v[190:193], v[92:95]
	s_waitcnt lgkmcnt(0)
	v_mfma_f32_16x16x32_bf16 v[88:91], v[232:235], v[190:193], v[88:91]
	v_mfma_f32_16x16x32_bf16 v[84:87], v[224:227], v[200:203], v[84:87]
	v_mfma_f32_16x16x32_bf16 v[80:83], v[232:235], v[200:203], v[80:83]
	v_mfma_f32_16x16x32_bf16 v[76:79], v[224:227], v[208:211], v[76:79]
	v_mfma_f32_16x16x32_bf16 v[72:75], v[232:235], v[208:211], v[72:75]
	v_mfma_f32_16x16x32_bf16 v[68:71], v[224:227], v[216:219], v[68:71]
	v_mfma_f32_16x16x32_bf16 v[64:67], v[232:235], v[216:219], v[64:67]
	s_setprio 0
	v_readfirstlane_b32 s48, v138
	s_add_i32 s47, s45, 0x100
	s_mov_b32 m0, s48
	v_readfirstlane_b32 s48, v140
	s_barrier
	ds_read_b128 v[186:189], v167 offset:16384
	ds_read_b128 v[190:193], v167 offset:17408
	ds_read_b128 v[196:199], v168 offset:16384
	ds_read_b128 v[200:203], v168 offset:17408
	ds_read_b128 v[204:207], v169 offset:16384
	ds_read_b128 v[208:211], v169 offset:17408
	ds_read_b128 v[212:215], v170 offset:16384
	ds_read_b128 v[216:219], v170 offset:17408
	buffer_load_dwordx4 v139, s[12:15], s47 offen lds
	s_mov_b32 m0, s48
	s_nop 0
	buffer_load_dwordx4 v141, s[12:15], s47 offen lds
	s_barrier
	s_waitcnt lgkmcnt(0)
	s_setprio 1
	s_waitcnt lgkmcnt(7)
	v_mfma_f32_16x16x32_bf16 v[60:63], v[130:133], v[186:189], v[60:63]
	v_mfma_f32_16x16x32_bf16 v[56:59], v[178:181], v[186:189], v[56:59]
	s_waitcnt lgkmcnt(5)
	v_mfma_f32_16x16x32_bf16 v[52:55], v[130:133], v[196:199], v[52:55]
	v_mfma_f32_16x16x32_bf16 v[48:51], v[178:181], v[196:199], v[48:51]
	s_waitcnt lgkmcnt(3)
	v_mfma_f32_16x16x32_bf16 v[44:47], v[130:133], v[204:207], v[44:47]
	v_mfma_f32_16x16x32_bf16 v[40:43], v[178:181], v[204:207], v[40:43]
	s_waitcnt lgkmcnt(1)
	v_mfma_f32_16x16x32_bf16 v[36:39], v[130:133], v[212:215], v[36:39]
	v_mfma_f32_16x16x32_bf16 v[32:35], v[178:181], v[212:215], v[32:35]
	v_mfma_f32_16x16x32_bf16 v[60:63], v[174:177], v[190:193], v[60:63]
	v_mfma_f32_16x16x32_bf16 v[56:59], v[182:185], v[190:193], v[56:59]
	v_mfma_f32_16x16x32_bf16 v[52:55], v[174:177], v[200:203], v[52:55]
	v_mfma_f32_16x16x32_bf16 v[48:51], v[182:185], v[200:203], v[48:51]
	v_mfma_f32_16x16x32_bf16 v[44:47], v[174:177], v[208:211], v[44:47]
	v_mfma_f32_16x16x32_bf16 v[40:43], v[182:185], v[208:211], v[40:43]
	s_waitcnt lgkmcnt(0)
	v_mfma_f32_16x16x32_bf16 v[36:39], v[174:177], v[216:219], v[36:39]
	v_mfma_f32_16x16x32_bf16 v[32:35], v[182:185], v[216:219], v[32:35]
	s_setprio 0
	s_barrier
; #define WAIT_V(n) asm volatile("s_waitcnt vmcnt(" #n ")" ::: "memory")
; #define WAIT_L(n) asm volatile("s_waitcnt lgkmcnt(" #n ")" ::: "memory")
; #define BAR __builtin_amdgcn_s_barrier()
; #define SCHED __builtin_amdgcn_sched_barrier(0)
; template <int EPI>
; __device__ void gemm8_phase(const Params& p, const u16* __restrict__ A, const u16* __restrict__ Bt, const int K, const int nN,
;                             unsigned char* smem, const int rep) {
;     ...
;       WAIT_V(6); BAR; MMA(1, 1, At, B1); BAR;
;       LDB(B0, 1, 0); SCHED; LDA(At, 1, 0); STAGE(SA(0, 1), A, brow + HALF, t + 2);
;       WAIT_L(8); BAR; WAIT_L(0); MMA(0, 0, At, B0); BAR; SCHED;
;       LDB(B1, 1, 1); STAGE(SB(1, 0), Bt, bcol, t + 3);
;       BAR; WAIT_L(0); MMA(0, 1, At, B1); BAR;
;       LDA(At, 1, 1); STAGE(SA(1, 0), A, brow, t + 3);
;       BAR; WAIT_L(0); MMA(1, 0, At, B0); BAR; SCHED;
	v_readfirstlane_b32 s48, v154
	s_add_i32 s47, s46, 0x40100
	s_mov_b32 m0, s48
	v_readfirstlane_b32 s48, v155
	buffer_load_dwordx4 v139, s[8:11], s47 offen lds
	s_mov_b32 m0, s48
	s_nop 0
	buffer_load_dwordx4 v141, s[8:11], s47 offen lds
	s_waitcnt vmcnt(6)
	s_barrier
	s_setprio 1
	v_mfma_f32_16x16x32_bf16 v[28:31], v[220:223], v[186:189], v[28:31]
	v_mfma_f32_16x16x32_bf16 v[24:27], v[228:231], v[186:189], v[24:27]
	v_mfma_f32_16x16x32_bf16 v[20:23], v[220:223], v[196:199], v[20:23]
	v_mfma_f32_16x16x32_bf16 v[16:19], v[228:231], v[196:199], v[16:19]
	v_mfma_f32_16x16x32_bf16 v[12:15], v[220:223], v[204:207], v[12:15]
	v_mfma_f32_16x16x32_bf16 v[8:11], v[228:231], v[204:207], v[8:11]
	v_mfma_f32_16x16x32_bf16 v[4:7], v[220:223], v[212:215], v[4:7]
	v_mfma_f32_16x16x32_bf16 v[0:3], v[228:231], v[212:215], v[0:3]
	v_mfma_f32_16x16x32_bf16 v[28:31], v[224:227], v[190:193], v[28:31]
	v_mfma_f32_16x16x32_bf16 v[24:27], v[232:235], v[190:193], v[24:27]
	v_mfma_f32_16x16x32_bf16 v[20:23], v[224:227], v[200:203], v[20:23]
	v_mfma_f32_16x16x32_bf16 v[16:19], v[232:235], v[200:203], v[16:19]
	v_mfma_f32_16x16x32_bf16 v[12:15], v[224:227], v[208:211], v[12:15]
	v_mfma_f32_16x16x32_bf16 v[8:11], v[232:235], v[208:211], v[8:11]
	v_mfma_f32_16x16x32_bf16 v[4:7], v[224:227], v[216:219], v[4:7]
	v_mfma_f32_16x16x32_bf16 v[0:3], v[232:235], v[216:219], v[0:3]
	s_setprio 0
	s_barrier
	ds_read_b128 v[130:133], v172
	ds_read_b128 v[174:177], v172 offset:1024
	ds_read_b128 v[178:181], v172 offset:2048
	ds_read_b128 v[182:185], v172 offset:3072
	v_readfirstlane_b32 s48, v156
	s_add_i32 s47, s45, 0x40100
	s_mov_b32 m0, s48
	v_readfirstlane_b32 s48, v157
	ds_read_b128 v[186:189], v167 offset:32768
	ds_read_b128 v[190:193], v167 offset:33792
	ds_read_b128 v[196:199], v168 offset:32768
	ds_read_b128 v[200:203], v168 offset:33792
	ds_read_b128 v[204:207], v169 offset:32768
	ds_read_b128 v[208:211], v169 offset:33792
	ds_read_b128 v[212:215], v170 offset:32768
	ds_read_b128 v[216:219], v170 offset:33792
	buffer_load_dwordx4 v139, s[12:15], s47 offen lds
	s_mov_b32 m0, s48
	s_nop 0
	buffer_load_dwordx4 v141, s[12:15], s47 offen lds
	s_waitcnt lgkmcnt(8)
	s_barrier
	s_waitcnt lgkmcnt(0)
	s_setprio 1
	s_waitcnt lgkmcnt(7)
	v_mfma_f32_16x16x32_bf16 v[124:127], v[130:133], v[186:189], v[124:127]
	v_mfma_f32_16x16x32_bf16 v[120:123], v[178:181], v[186:189], v[120:123]
	s_waitcnt lgkmcnt(5)
	v_mfma_f32_16x16x32_bf16 v[116:119], v[130:133], v[196:199], v[116:119]
	v_mfma_f32_16x16x32_bf16 v[112:115], v[178:181], v[196:199], v[112:115]
	s_waitcnt lgkmcnt(3)
	v_mfma_f32_16x16x32_bf16 v[108:111], v[130:133], v[204:207], v[108:111]
	v_mfma_f32_16x16x32_bf16 v[104:107], v[178:181], v[204:207], v[104:107]
	s_waitcnt lgkmcnt(1)
	v_mfma_f32_16x16x32_bf16 v[100:103], v[130:133], v[212:215], v[100:103]
	v_mfma_f32_16x16x32_bf16 v[96:99], v[178:181], v[212:215], v[96:99]
	v_mfma_f32_16x16x32_bf16 v[124:127], v[174:177], v[190:193], v[124:127]
	v_mfma_f32_16x16x32_bf16 v[120:123], v[182:185], v[190:193], v[120:123]
	v_mfma_f32_16x16x32_bf16 v[116:119], v[174:177], v[200:203], v[116:119]
	v_mfma_f32_16x16x32_bf16 v[112:115], v[182:185], v[200:203], v[112:115]
	v_mfma_f32_16x16x32_bf16 v[108:111], v[174:177], v[208:211], v[108:111]
	v_mfma_f32_16x16x32_bf16 v[104:107], v[182:185], v[208:211], v[104:107]
	s_waitcnt lgkmcnt(0)
	v_mfma_f32_16x16x32_bf16 v[100:103], v[174:177], v[216:219], v[100:103]
	v_mfma_f32_16x16x32_bf16 v[96:99], v[182:185], v[216:219], v[96:99]
	s_setprio 0
	s_barrier
	v_readfirstlane_b32 s48, v158
	s_add_i32 s47, s46, 0x180
	s_mov_b32 m0, s48
	v_readfirstlane_b32 s48, v159
	ds_read_b128 v[220:223], v173
	ds_read_b128 v[224:227], v173 offset:1024
	ds_read_b128 v[228:231], v173 offset:2048
	ds_read_b128 v[232:235], v173 offset:3072
	buffer_load_dwordx4 v139, s[8:11], s47 offen lds
	s_mov_b32 m0, s48
	s_nop 0
	buffer_load_dwordx4 v141, s[8:11], s47 offen lds
	s_barrier
	s_waitcnt lgkmcnt(0)
	s_setprio 1
	s_waitcnt lgkmcnt(3)
	v_mfma_f32_16x16x32_bf16 v[92:95], v[220:223], v[186:189], v[92:95]
	s_waitcnt lgkmcnt(1)
	v_mfma_f32_16x16x32_bf16 v[88:91], v[228:231], v[186:189], v[88:91]
	v_mfma_f32_16x16x32_bf16 v[84:87], v[220:223], v[196:199], v[84:87]
	v_mfma_f32_16x16x32_bf16 v[80:83], v[228:231], v[196:199], v[80:83]
	v_mfma_f32_16x16x32_bf16 v[76:79], v[220:223], v[204:207], v[76:79]
	v_mfma_f32_16x16x32_bf16 v[72:75], v[228:231], v[204:207], v[72:75]
	v_mfma_f32_16x16x32_bf16 v[68:71], v[220:223], v[212:215], v[68:71]
	v_mfma_f32_16x16x32_bf16 v[64:67], v[228:231], v[212:215], v[64:67]
	v_mfma_f32_16x16x32_bf16 v[92:95], v[224:227], v[190:193], v[92:95]
	s_waitcnt lgkmcnt(0)
	v_mfma_f32_16x16x32_bf16 v[88:91], v[232:235], v[190:193], v[88:91]
	v_mfma_f32_16x16x32_bf16 v[84:87], v[224:227], v[200:203], v[84:87]
	v_mfma_f32_16x16x32_bf16 v[80:83], v[232:235], v[200:203], v[80:83]
	v_mfma_f32_16x16x32_bf16 v[76:79], v[224:227], v[208:211], v[76:79]
	v_mfma_f32_16x16x32_bf16 v[72:75], v[232:235], v[208:211], v[72:75]
	v_mfma_f32_16x16x32_bf16 v[68:71], v[224:227], v[216:219], v[68:71]
	v_mfma_f32_16x16x32_bf16 v[64:67], v[232:235], v[216:219], v[64:67]
	s_setprio 0
	v_readfirstlane_b32 s47, v160
	s_addk_i32 s45, 0x180
	s_mov_b32 m0, s47
	v_readfirstlane_b32 s47, v161
	s_barrier
	ds_read_b128 v[186:189], v167 offset:49152
	ds_read_b128 v[190:193], v167 offset:50176
	ds_read_b128 v[196:199], v168 offset:49152
	ds_read_b128 v[200:203], v168 offset:50176
	ds_read_b128 v[204:207], v169 offset:49152
	ds_read_b128 v[208:211], v169 offset:50176
	ds_read_b128 v[212:215], v170 offset:49152
	ds_read_b128 v[216:219], v170 offset:50176
	buffer_load_dwordx4 v139, s[12:15], s45 offen lds
	s_mov_b32 m0, s47
	s_nop 0
	buffer_load_dwordx4 v141, s[12:15], s45 offen lds
	s_barrier
; #define WAIT_V(n) asm volatile("s_waitcnt vmcnt(" #n ")" ::: "memory")
; #define WAIT_L(n) asm volatile("s_waitcnt lgkmcnt(" #n ")" ::: "memory")
; #define BAR __builtin_amdgcn_s_barrier()
; #define SCHED __builtin_amdgcn_sched_barrier(0)
; template <int EPI>
; __device__ void gemm8_phase(const Params& p, const u16* __restrict__ A, const u16* __restrict__ Bt, const int K, const int nN,
;                             unsigned char* smem, const int rep) {
;     ...
;       STAGE(SB(1, 1), Bt, bcol + HALF, t + 3);
;       WAIT_V(6); BAR; MMA(1, 1, At, B1); BAR;
;     }
;     {
;       LDB(B0, 0, 0); LDA(At, 0, 0); STAGE(SA(1, 1), A, brow + HALF, nt - 1);
;       BAR; WAIT_L(0); MMA(0, 0, At, B0); BAR; SCHED;
;       LDB(B1, 0, 1); BAR; WAIT_L(0); MMA(0, 1, At, B1); BAR; SCHED;
;       LDA(At, 0, 1); WAIT_V(4); BAR; WAIT_L(0); MMA(1, 0, At, B0); MMA(1, 1, At, B1); BAR; SCHED;
	s_waitcnt lgkmcnt(0)
	s_setprio 1
	s_waitcnt lgkmcnt(7)
	v_mfma_f32_16x16x32_bf16 v[60:63], v[130:133], v[186:189], v[60:63]
	v_mfma_f32_16x16x32_bf16 v[56:59], v[178:181], v[186:189], v[56:59]
	s_waitcnt lgkmcnt(5)
	v_mfma_f32_16x16x32_bf16 v[52:55], v[130:133], v[196:199], v[52:55]
	v_mfma_f32_16x16x32_bf16 v[48:51], v[178:181], v[196:199], v[48:51]
	s_waitcnt lgkmcnt(3)
	v_mfma_f32_16x16x32_bf16 v[44:47], v[130:133], v[204:207], v[44:47]
	v_mfma_f32_16x16x32_bf16 v[40:43], v[178:181], v[204:207], v[40:43]
	s_waitcnt lgkmcnt(1)
	v_mfma_f32_16x16x32_bf16 v[36:39], v[130:133], v[212:215], v[36:39]
	v_mfma_f32_16x16x32_bf16 v[32:35], v[178:181], v[212:215], v[32:35]
	v_mfma_f32_16x16x32_bf16 v[60:63], v[174:177], v[190:193], v[60:63]
	v_mfma_f32_16x16x32_bf16 v[56:59], v[182:185], v[190:193], v[56:59]
	v_mfma_f32_16x16x32_bf16 v[52:55], v[174:177], v[200:203], v[52:55]
	v_mfma_f32_16x16x32_bf16 v[48:51], v[182:185], v[200:203], v[48:51]
	v_mfma_f32_16x16x32_bf16 v[44:47], v[174:177], v[208:211], v[44:47]
	v_mfma_f32_16x16x32_bf16 v[40:43], v[182:185], v[208:211], v[40:43]
	s_waitcnt lgkmcnt(0)
	v_mfma_f32_16x16x32_bf16 v[36:39], v[174:177], v[216:219], v[36:39]
	v_mfma_f32_16x16x32_bf16 v[32:35], v[182:185], v[216:219], v[32:35]
	s_setprio 0
	s_barrier
	v_readfirstlane_b32 s45, v162
	s_add_i32 s46, s46, 0x40180
	s_mov_b32 m0, s45
	v_readfirstlane_b32 s45, v163
	buffer_load_dwordx4 v139, s[8:11], s46 offen lds
	s_mov_b32 m0, s45
	s_nop 0
	buffer_load_dwordx4 v141, s[8:11], s46 offen lds
	s_waitcnt vmcnt(6)
	s_barrier
	s_setprio 1
	v_mfma_f32_16x16x32_bf16 v[28:31], v[220:223], v[186:189], v[28:31]
	v_mfma_f32_16x16x32_bf16 v[24:27], v[228:231], v[186:189], v[24:27]
	v_mfma_f32_16x16x32_bf16 v[20:23], v[220:223], v[196:199], v[20:23]
	v_mfma_f32_16x16x32_bf16 v[16:19], v[228:231], v[196:199], v[16:19]
	v_mfma_f32_16x16x32_bf16 v[12:15], v[220:223], v[204:207], v[12:15]
	v_mfma_f32_16x16x32_bf16 v[8:11], v[228:231], v[204:207], v[8:11]
	v_mfma_f32_16x16x32_bf16 v[4:7], v[220:223], v[212:215], v[4:7]
	v_mfma_f32_16x16x32_bf16 v[0:3], v[228:231], v[212:215], v[0:3]
	v_mfma_f32_16x16x32_bf16 v[28:31], v[224:227], v[190:193], v[28:31]
	v_mfma_f32_16x16x32_bf16 v[24:27], v[232:235], v[190:193], v[24:27]
	v_mfma_f32_16x16x32_bf16 v[20:23], v[224:227], v[200:203], v[20:23]
	v_mfma_f32_16x16x32_bf16 v[16:19], v[232:235], v[200:203], v[16:19]
	v_mfma_f32_16x16x32_bf16 v[12:15], v[224:227], v[208:211], v[12:15]
	v_mfma_f32_16x16x32_bf16 v[8:11], v[232:235], v[208:211], v[8:11]
	v_mfma_f32_16x16x32_bf16 v[4:7], v[224:227], v[216:219], v[4:7]
	v_mfma_f32_16x16x32_bf16 v[0:3], v[232:235], v[216:219], v[0:3]
	s_setprio 0
	s_add_i32 s33, s33, 2
	s_addk_i32 s44, 0x100
	s_cmp_lt_u32 s33, 12
	s_barrier
	s_cbranch_scc1 .LBB0_202
	v_readfirstlane_b32 s6, v164
	s_or_b32 s5, s5, 0x40780
	s_mov_b32 m0, s6
	v_readfirstlane_b32 s6, v165
	ds_read_b128 v[130:133], v166
	ds_read_b128 v[174:177], v166 offset:1024
	ds_read_b128 v[178:181], v166 offset:2048
	ds_read_b128 v[182:185], v166 offset:3072
	ds_read_b128 v[186:189], v167
	ds_read_b128 v[190:193], v167 offset:1024
	ds_read_b128 v[196:199], v168
	ds_read_b128 v[200:203], v168 offset:1024
	ds_read_b128 v[204:207], v169
	ds_read_b128 v[208:211], v169 offset:1024
	ds_read_b128 v[212:215], v170
	ds_read_b128 v[216:219], v170 offset:1024
	buffer_load_dwordx4 v139, s[12:15], s5 offen lds
	s_mov_b32 m0, s6
	s_nop 0
	buffer_load_dwordx4 v141, s[12:15], s5 offen lds
	s_barrier
	s_waitcnt lgkmcnt(0)
	s_setprio 1
	s_waitcnt lgkmcnt(7)
	v_mfma_f32_16x16x32_bf16 v[124:127], v[130:133], v[186:189], v[124:127]
	s_waitcnt lgkmcnt(5)
	v_mfma_f32_16x16x32_bf16 v[116:119], v[130:133], v[196:199], v[116:119]
	v_mfma_f32_16x16x32_bf16 v[112:115], v[178:181], v[196:199], v[112:115]
	s_waitcnt lgkmcnt(1)
	v_mfma_f32_16x16x32_bf16 v[100:103], v[130:133], v[212:215], v[100:103]
	v_mfma_f32_16x16x32_bf16 v[96:99], v[178:181], v[212:215], v[96:99]
	v_mfma_f32_16x16x32_bf16 v[124:127], v[174:177], v[190:193], v[124:127]
	v_mfma_f32_16x16x32_bf16 v[120:123], v[178:181], v[186:189], v[120:123]
	v_mfma_f32_16x16x32_bf16 v[116:119], v[174:177], v[200:203], v[116:119]
	v_mfma_f32_16x16x32_bf16 v[112:115], v[182:185], v[200:203], v[112:115]
	v_mfma_f32_16x16x32_bf16 v[108:111], v[130:133], v[204:207], v[108:111]
	v_mfma_f32_16x16x32_bf16 v[104:107], v[178:181], v[204:207], v[104:107]
	s_waitcnt lgkmcnt(0)
	v_mfma_f32_16x16x32_bf16 v[100:103], v[174:177], v[216:219], v[100:103]
	v_mfma_f32_16x16x32_bf16 v[96:99], v[182:185], v[216:219], v[96:99]
	v_mfma_f32_16x16x32_bf16 v[220:223], v[182:185], v[190:193], v[120:123]
	v_mfma_f32_16x16x32_bf16 v[224:227], v[174:177], v[208:211], v[108:111]
	v_mfma_f32_16x16x32_bf16 v[228:231], v[182:185], v[208:211], v[104:107]
	s_setprio 0
	s_barrier
	s_nop 0
	ds_read_b128 v[104:107], v171
	ds_read_b128 v[108:111], v171 offset:1024
	ds_read_b128 v[120:123], v171 offset:2048
	ds_read_b128 v[232:235], v171 offset:3072
	s_barrier
	s_waitcnt lgkmcnt(0)
	s_setprio 1
	s_waitcnt lgkmcnt(3)
	v_mfma_f32_16x16x32_bf16 v[84:87], v[104:107], v[196:199], v[84:87]
	s_waitcnt lgkmcnt(1)
	v_mfma_f32_16x16x32_bf16 v[80:83], v[120:123], v[196:199], v[80:83]
	v_mfma_f32_16x16x32_bf16 v[68:71], v[104:107], v[212:215], v[68:71]
	v_mfma_f32_16x16x32_bf16 v[92:95], v[104:107], v[186:189], v[92:95]
	v_mfma_f32_16x16x32_bf16 v[88:91], v[120:123], v[186:189], v[88:91]
	v_mfma_f32_16x16x32_bf16 v[84:87], v[108:111], v[200:203], v[84:87]
	s_waitcnt lgkmcnt(0)
	v_mfma_f32_16x16x32_bf16 v[80:83], v[232:235], v[200:203], v[80:83]
	v_mfma_f32_16x16x32_bf16 v[76:79], v[104:107], v[204:207], v[76:79]
	v_mfma_f32_16x16x32_bf16 v[72:75], v[120:123], v[204:207], v[72:75]
	v_mfma_f32_16x16x32_bf16 v[68:71], v[108:111], v[216:219], v[68:71]
	v_mfma_f32_16x16x32_bf16 v[64:67], v[120:123], v[212:215], v[64:67]
	v_mfma_f32_16x16x32_bf16 v[236:239], v[108:111], v[190:193], v[92:95]
	v_mfma_f32_16x16x32_bf16 v[186:189], v[232:235], v[190:193], v[88:91]
	v_mfma_f32_16x16x32_bf16 v[190:193], v[108:111], v[208:211], v[76:79]
	v_mfma_f32_16x16x32_bf16 v[196:199], v[232:235], v[208:211], v[72:75]
	v_mfma_f32_16x16x32_bf16 v[200:203], v[232:235], v[216:219], v[64:67]
	s_setprio 0
	s_barrier
; #define WAIT_V(n) asm volatile("s_waitcnt vmcnt(" #n ")" ::: "memory")
; #define WAIT_L(n) asm volatile("s_waitcnt lgkmcnt(" #n ")" ::: "memory")
; #define BAR __builtin_amdgcn_s_barrier()
; #define SCHED __builtin_amdgcn_sched_barrier(0)
; template <int EPI>
; __device__ void gemm8_phase(const Params& p, const u16* __restrict__ A, const u16* __restrict__ Bt, const int K, const int nN,
;                             unsigned char* smem, const int rep) {
;     ...
;       LDA(At, 0, 1); WAIT_V(4); BAR; WAIT_L(0); MMA(1, 0, At, B0); MMA(1, 1, At, B1); BAR; SCHED;
;     }
;     {
;       LDB(B0, 1, 0); LDA(At, 1, 0); WAIT_V(2); BAR; WAIT_L(0); MMA(0, 0, At, B0); BAR; SCHED;
;       LDB(B1, 1, 1); WAIT_V(0); BAR; WAIT_L(0); MMA(0, 1, At, B1); BAR; SCHED;
;       LDA(At, 1, 1); BAR; WAIT_L(0); MMA(1, 0, At, B0); MMA(1, 1, At, B1); BAR; SCHED;
	s_nop 0
	ds_read_b128 v[64:67], v167 offset:16384
	ds_read_b128 v[72:75], v167 offset:17408
	ds_read_b128 v[76:79], v168 offset:16384
	ds_read_b128 v[88:91], v168 offset:17408
	ds_read_b128 v[92:95], v169 offset:16384
	ds_read_b128 v[204:207], v169 offset:17408
	ds_read_b128 v[208:211], v170 offset:16384
	ds_read_b128 v[212:215], v170 offset:17408
	s_waitcnt vmcnt(4)
	s_barrier
	s_waitcnt lgkmcnt(0)
	s_setprio 1
	s_waitcnt lgkmcnt(7)
	v_mfma_f32_16x16x32_bf16 v[60:63], v[130:133], v[64:67], v[60:63]
	s_waitcnt lgkmcnt(5)
	v_mfma_f32_16x16x32_bf16 v[52:55], v[130:133], v[76:79], v[52:55]
	v_mfma_f32_16x16x32_bf16 v[48:51], v[178:181], v[76:79], v[48:51]
	s_waitcnt lgkmcnt(1)
	v_mfma_f32_16x16x32_bf16 v[36:39], v[130:133], v[208:211], v[36:39]
	v_mfma_f32_16x16x32_bf16 v[32:35], v[178:181], v[208:211], v[32:35]
	v_mfma_f32_16x16x32_bf16 v[60:63], v[174:177], v[72:75], v[60:63]
	v_mfma_f32_16x16x32_bf16 v[56:59], v[178:181], v[64:67], v[56:59]
	v_mfma_f32_16x16x32_bf16 v[52:55], v[174:177], v[88:91], v[52:55]
	v_mfma_f32_16x16x32_bf16 v[48:51], v[182:185], v[88:91], v[48:51]
	v_mfma_f32_16x16x32_bf16 v[44:47], v[130:133], v[92:95], v[44:47]
	v_mfma_f32_16x16x32_bf16 v[40:43], v[178:181], v[92:95], v[40:43]
	s_waitcnt lgkmcnt(0)
	v_mfma_f32_16x16x32_bf16 v[36:39], v[174:177], v[212:215], v[36:39]
	v_mfma_f32_16x16x32_bf16 v[32:35], v[182:185], v[212:215], v[32:35]
	v_mfma_f32_16x16x32_bf16 v[216:219], v[182:185], v[72:75], v[56:59]
	v_mfma_f32_16x16x32_bf16 v[240:243], v[174:177], v[204:207], v[44:47]
	v_mfma_f32_16x16x32_bf16 v[244:247], v[182:185], v[204:207], v[40:43]
	s_setprio 0
	s_setprio 1
	v_mfma_f32_16x16x32_bf16 v[20:23], v[104:107], v[76:79], v[20:23]
	v_mfma_f32_16x16x32_bf16 v[16:19], v[120:123], v[76:79], v[16:19]
	v_mfma_f32_16x16x32_bf16 v[4:7], v[104:107], v[208:211], v[4:7]
	v_mfma_f32_16x16x32_bf16 v[28:31], v[104:107], v[64:67], v[28:31]
	v_mfma_f32_16x16x32_bf16 v[24:27], v[120:123], v[64:67], v[24:27]
	v_mfma_f32_16x16x32_bf16 v[20:23], v[108:111], v[88:91], v[20:23]
	v_mfma_f32_16x16x32_bf16 v[16:19], v[232:235], v[88:91], v[16:19]
	v_mfma_f32_16x16x32_bf16 v[12:15], v[104:107], v[92:95], v[12:15]
	v_mfma_f32_16x16x32_bf16 v[8:11], v[120:123], v[92:95], v[8:11]
	v_mfma_f32_16x16x32_bf16 v[4:7], v[108:111], v[212:215], v[4:7]
	v_mfma_f32_16x16x32_bf16 v[0:3], v[120:123], v[208:211], v[0:3]
	v_mfma_f32_16x16x32_bf16 v[130:133], v[108:111], v[72:75], v[28:31]
	v_mfma_f32_16x16x32_bf16 v[174:177], v[232:235], v[72:75], v[24:27]
	v_mfma_f32_16x16x32_bf16 v[178:181], v[108:111], v[204:207], v[12:15]
	v_mfma_f32_16x16x32_bf16 v[182:185], v[232:235], v[204:207], v[8:11]
	v_mfma_f32_16x16x32_bf16 v[204:207], v[232:235], v[212:215], v[0:3]
	s_setprio 0
	s_barrier
	s_nop 0
	ds_read_b128 v[0:3], v172
	ds_read_b128 v[8:11], v172 offset:1024
	ds_read_b128 v[12:15], v172 offset:2048
	ds_read_b128 v[208:211], v172 offset:3072
	ds_read_b128 v[24:27], v167 offset:32768
	ds_read_b128 v[28:31], v167 offset:33792
	ds_read_b128 v[40:43], v168 offset:32768
	ds_read_b128 v[44:47], v168 offset:33792
	ds_read_b128 v[56:59], v169 offset:32768
	ds_read_b128 v[64:67], v169 offset:33792
	ds_read_b128 v[212:215], v170 offset:32768
	ds_read_b128 v[232:235], v170 offset:33792
	s_waitcnt vmcnt(2)
	s_barrier
	s_waitcnt lgkmcnt(0)
	s_setprio 1
	s_waitcnt lgkmcnt(7)
	v_mfma_f32_16x16x32_bf16 v[72:75], v[0:3], v[24:27], v[124:127]
	s_waitcnt lgkmcnt(6)
	v_mfma_f32_16x16x32_bf16 v[120:123], v[8:11], v[28:31], v[72:75]
	v_mfma_f32_16x16x32_bf16 v[72:75], v[12:15], v[24:27], v[220:223]
	v_mfma_f32_16x16x32_bf16 v[124:127], v[208:211], v[28:31], v[72:75]
	s_waitcnt lgkmcnt(5)
	v_mfma_f32_16x16x32_bf16 v[72:75], v[0:3], v[40:43], v[116:119]
	s_waitcnt lgkmcnt(4)
	v_mfma_f32_16x16x32_bf16 v[104:107], v[8:11], v[44:47], v[72:75]
	v_mfma_f32_16x16x32_bf16 v[72:75], v[12:15], v[40:43], v[112:115]
	v_mfma_f32_16x16x32_bf16 v[108:111], v[208:211], v[44:47], v[72:75]
	s_waitcnt lgkmcnt(3)
	v_mfma_f32_16x16x32_bf16 v[72:75], v[0:3], v[56:59], v[224:227]
	s_waitcnt lgkmcnt(2)
	v_mfma_f32_16x16x32_bf16 v[88:91], v[8:11], v[64:67], v[72:75]
	v_mfma_f32_16x16x32_bf16 v[72:75], v[12:15], v[56:59], v[228:231]
	v_mfma_f32_16x16x32_bf16 v[92:95], v[208:211], v[64:67], v[72:75]
	s_waitcnt lgkmcnt(1)
	v_mfma_f32_16x16x32_bf16 v[72:75], v[0:3], v[212:215], v[100:103]
	v_mfma_f32_16x16x32_bf16 v[76:79], v[12:15], v[212:215], v[96:99]
	s_waitcnt lgkmcnt(0)
	v_mfma_f32_16x16x32_bf16 v[72:75], v[8:11], v[232:235], v[72:75]
	v_mfma_f32_16x16x32_bf16 v[76:79], v[208:211], v[232:235], v[76:79]
	s_setprio 0
	s_barrier
	ds_read_b128 v[220:223], v173
	ds_read_b128 v[224:227], v173 offset:1024
	ds_read_b128 v[228:231], v173 offset:2048
	ds_read_b128 v[248:251], v173 offset:3072
	s_waitcnt vmcnt(0)
	s_barrier
	s_waitcnt lgkmcnt(0)
	s_setprio 1
	s_waitcnt lgkmcnt(3)
	v_mfma_f32_16x16x32_bf16 v[96:99], v[220:223], v[24:27], v[236:239]
	s_waitcnt lgkmcnt(1)
	v_mfma_f32_16x16x32_bf16 v[24:27], v[228:231], v[24:27], v[186:189]
	s_waitcnt lgkmcnt(0)
	v_mfma_f32_16x16x32_bf16 v[116:119], v[248:251], v[28:31], v[24:27]
	v_mfma_f32_16x16x32_bf16 v[24:27], v[220:223], v[40:43], v[84:87]
	v_mfma_f32_16x16x32_bf16 v[112:115], v[224:227], v[28:31], v[96:99]
	v_mfma_f32_16x16x32_bf16 v[96:99], v[224:227], v[44:47], v[24:27]
	v_mfma_f32_16x16x32_bf16 v[24:27], v[228:231], v[40:43], v[80:83]
	v_mfma_f32_16x16x32_bf16 v[100:103], v[248:251], v[44:47], v[24:27]
	v_mfma_f32_16x16x32_bf16 v[24:27], v[220:223], v[56:59], v[190:193]
	v_mfma_f32_16x16x32_bf16 v[80:83], v[224:227], v[64:67], v[24:27]
	v_mfma_f32_16x16x32_bf16 v[24:27], v[228:231], v[56:59], v[196:199]
	v_mfma_f32_16x16x32_bf16 v[84:87], v[248:251], v[64:67], v[24:27]
	v_mfma_f32_16x16x32_bf16 v[24:27], v[220:223], v[212:215], v[68:71]
	v_mfma_f32_16x16x32_bf16 v[64:67], v[224:227], v[232:235], v[24:27]
	v_mfma_f32_16x16x32_bf16 v[24:27], v[228:231], v[212:215], v[200:203]
	v_mfma_f32_16x16x32_bf16 v[68:71], v[248:251], v[232:235], v[24:27]
	s_setprio 0
	s_barrier
; #define WAIT_V(n) asm volatile("s_waitcnt vmcnt(" #n ")" ::: "memory")
; #define WAIT_L(n) asm volatile("s_waitcnt lgkmcnt(" #n ")" ::: "memory")
; #define BAR __builtin_amdgcn_s_barrier()
; #define SCHED __builtin_amdgcn_sched_barrier(0)
; template <int EPI>
; __device__ void gemm8_phase(const Params& p, const u16* __restrict__ A, const u16* __restrict__ Bt, const int K, const int nN,
;                             unsigned char* smem, const int rep) {
;     ...
;       LDB(B0, 1, 0); LDA(At, 1, 0); WAIT_V(2); BAR; WAIT_L(0); MMA(0, 0, At, B0); BAR; SCHED;
;       LDB(B1, 1, 1); WAIT_V(0); BAR; WAIT_L(0); MMA(0, 1, At, B1); BAR; SCHED;
;       LDA(At, 1, 1); BAR; WAIT_L(0); MMA(1, 0, At, B0); MMA(1, 1, At, B1); BAR; SCHED;
;     }
;     if (wr == 0) BAR;
;     u16* projb = (u16*)(p.ws + OFF_PROJ);
; #pragma unroll
;     for (int ai = 0; ai < 2; ++ai)
; #pragma unroll
;       for (int m = 0; m < 4; ++m) {
;         if (EPI == 0 && bcol < 2048) {
;           const float2* rope = (const float2*)(p.ws + OFF_ROPE);
; #pragma unroll
;           for (int bj = 0; bj < 2; ++bj) {
;             __builtin_amdgcn_sched_barrier(0);
;             const int pc = bcol + bj * HALF + wc * 32;
;             const int i = ((pc & 255) >> 5) * 16 + fr;
;     ...
;         } else {
; #pragma unroll
;           for (int j = 0; j < 4; ++j) {
;             __builtin_amdgcn_sched_barrier(0);
;             const int row = brow + ai * HALF + wr * 64 + m * 16 + fq * 4 + j;
;             u16* proj = projb + (size_t)row * PROJ_LD;
;             float* cvo = nullptr;
;             if (EPI == 2 && bcol >= 2048) {
;               if (row < NPROMPT) {
;                 const int t = row & 2047;
;                 if (t >= 2045) cvo = p.out + OUT_CONVP + ((size_t)(row >> 11) * 3 + (t - 2045)) * 4096;
;               } else {
;                 const int rs = row - NPROMPT, t = rs & 7;
;                 if (t >= 5) cvo = p.out + OUT_CONVS + ((size_t)(rs >> 3) * 3 + (t - 5)) * 4096;
;               }
;             }
; #pragma unroll
;             for (int bj = 0; bj < 2; ++bj)
; #pragma unroll
;               for (int n = 0; n < 2; ++n) {
;                 const int col = bcol + bj * HALF + wc * 32 + n * 16 + fr;
;                 const float a = acc[ai][bj][m][n][j];
;                 proj[col] = f2bf(a);
;                 if (EPI == 2 && cvo) cvo[col - 2048] = a;
;               }
;           }
	ds_read_b128 v[186:189], v167 offset:49152
	ds_read_b128 v[190:193], v167 offset:50176
	ds_read_b128 v[196:199], v168 offset:49152
	ds_read_b128 v[200:203], v168 offset:50176
	ds_read_b128 v[212:215], v169 offset:49152
	ds_read_b128 v[232:235], v169 offset:50176
	ds_read_b128 v[236:239], v170 offset:49152
	ds_read_b128 v[134:137], v170 offset:50176
	s_barrier
	s_waitcnt lgkmcnt(0)
	s_setprio 1
	s_waitcnt lgkmcnt(7)
	v_mfma_f32_16x16x32_bf16 v[24:27], v[0:3], v[186:189], v[60:63]
	s_waitcnt lgkmcnt(6)
	v_mfma_f32_16x16x32_bf16 v[56:59], v[8:11], v[190:193], v[24:27]
	v_mfma_f32_16x16x32_bf16 v[24:27], v[12:15], v[186:189], v[216:219]
	v_mfma_f32_16x16x32_bf16 v[60:63], v[208:211], v[190:193], v[24:27]
	s_waitcnt lgkmcnt(5)
	v_mfma_f32_16x16x32_bf16 v[24:27], v[0:3], v[196:199], v[52:55]
	s_waitcnt lgkmcnt(4)
	v_mfma_f32_16x16x32_bf16 v[40:43], v[8:11], v[200:203], v[24:27]
	v_mfma_f32_16x16x32_bf16 v[24:27], v[12:15], v[196:199], v[48:51]
	v_mfma_f32_16x16x32_bf16 v[44:47], v[208:211], v[200:203], v[24:27]
	s_waitcnt lgkmcnt(3)
	v_mfma_f32_16x16x32_bf16 v[24:27], v[0:3], v[212:215], v[240:243]
	s_waitcnt lgkmcnt(1)
	v_mfma_f32_16x16x32_bf16 v[0:3], v[0:3], v[236:239], v[36:39]
	v_mfma_f32_16x16x32_bf16 v[24:27], v[8:11], v[232:235], v[24:27]
	v_mfma_f32_16x16x32_bf16 v[28:31], v[12:15], v[212:215], v[244:247]
	s_waitcnt lgkmcnt(0)
	v_mfma_f32_16x16x32_bf16 v[8:11], v[8:11], v[134:137], v[0:3]
	v_mfma_f32_16x16x32_bf16 v[0:3], v[12:15], v[236:239], v[32:35]
	v_mfma_f32_16x16x32_bf16 v[28:31], v[208:211], v[232:235], v[28:31]
	v_mfma_f32_16x16x32_bf16 v[12:15], v[208:211], v[134:137], v[0:3]
	s_setprio 0
	s_setprio 1
	v_mfma_f32_16x16x32_bf16 v[0:3], v[220:223], v[186:189], v[130:133]
	v_mfma_f32_16x16x32_bf16 v[48:51], v[224:227], v[190:193], v[0:3]
	v_mfma_f32_16x16x32_bf16 v[0:3], v[228:231], v[186:189], v[174:177]
	v_mfma_f32_16x16x32_bf16 v[52:55], v[248:251], v[190:193], v[0:3]
	v_mfma_f32_16x16x32_bf16 v[0:3], v[220:223], v[196:199], v[20:23]
	v_mfma_f32_16x16x32_bf16 v[32:35], v[224:227], v[200:203], v[0:3]
	v_mfma_f32_16x16x32_bf16 v[0:3], v[228:231], v[196:199], v[16:19]
	v_mfma_f32_16x16x32_bf16 v[36:39], v[248:251], v[200:203], v[0:3]
	v_mfma_f32_16x16x32_bf16 v[0:3], v[220:223], v[212:215], v[178:181]
	v_mfma_f32_16x16x32_bf16 v[16:19], v[224:227], v[232:235], v[0:3]
	v_mfma_f32_16x16x32_bf16 v[0:3], v[228:231], v[212:215], v[182:185]
	v_mfma_f32_16x16x32_bf16 v[20:23], v[248:251], v[232:235], v[0:3]
	v_mfma_f32_16x16x32_bf16 v[0:3], v[220:223], v[236:239], v[4:7]
	v_mfma_f32_16x16x32_bf16 v[4:7], v[228:231], v[236:239], v[204:207]
	v_mfma_f32_16x16x32_bf16 v[0:3], v[224:227], v[134:137], v[0:3]
	v_mfma_f32_16x16x32_bf16 v[4:7], v[248:251], v[134:137], v[4:7]
	s_setprio 0
	s_barrier
	s_andn2_b64 vcc, exec, s[16:17]
	s_cbranch_vccnz .LBB0_205
	s_barrier
.LBB0_205:
	v_readlane_b32 s5, v255, 6
	s_cmp_lt_u32 s1, 8
	s_cselect_b32 s0, 1, 0
	s_lshl_b32 s33, s1, 9
	s_lshl_b32 s4, s4, 8
	s_lshr_b32 s6, s5, 2
	s_and_b32 s5, s5, 3
	s_lshl_b32 s6, s6, 6
	v_and_b32_e32 v176, 15, v195
	v_lshrrev_b32_e32 v177, 4, v195
	v_add_u32_e32 v178, s6, v176
	v_mul_u32_u24_e32 v179, 0x210, v178
	v_lshl_add_u32 v179, v177, 3, v179
	s_cmp_eq_u32 s0, 1
	s_cbranch_scc1 .Lg1_rope
	s_lshl_b32 s7, s5, 6
	v_add_u32_e32 v179, s7, v179
	v_add_u32_e32 v180, 0x10800, v179
	v_cvt_pk_bf16_f32 v120, v120, v121
	v_cvt_pk_bf16_f32 v121, v122, v123
	ds_write_b64 v179, v[120:121]
	v_cvt_pk_bf16_f32 v124, v124, v125
	v_cvt_pk_bf16_f32 v125, v126, v127
	ds_write_b64 v179, v[124:125] offset:32
	v_cvt_pk_bf16_f32 v112, v112, v113
	v_cvt_pk_bf16_f32 v113, v114, v115
	ds_write_b64 v179, v[112:113] offset:256
	v_cvt_pk_bf16_f32 v116, v116, v117
	v_cvt_pk_bf16_f32 v117, v118, v119
	ds_write_b64 v179, v[116:117] offset:288
	v_cvt_pk_bf16_f32 v104, v104, v105
	v_cvt_pk_bf16_f32 v105, v106, v107
	ds_write_b64 v179, v[104:105] offset:8448
	v_cvt_pk_bf16_f32 v108, v108, v109
	v_cvt_pk_bf16_f32 v109, v110, v111
	ds_write_b64 v179, v[108:109] offset:8480
	v_cvt_pk_bf16_f32 v96, v96, v97
	v_cvt_pk_bf16_f32 v97, v98, v99
	ds_write_b64 v179, v[96:97] offset:8704
	v_cvt_pk_bf16_f32 v100, v100, v101
	v_cvt_pk_bf16_f32 v101, v102, v103
	ds_write_b64 v179, v[100:101] offset:8736
	v_cvt_pk_bf16_f32 v88, v88, v89
	v_cvt_pk_bf16_f32 v89, v90, v91
	ds_write_b64 v179, v[88:89] offset:16896
	v_cvt_pk_bf16_f32 v92, v92, v93
	v_cvt_pk_bf16_f32 v93, v94, v95
	ds_write_b64 v179, v[92:93] offset:16928
	v_cvt_pk_bf16_f32 v80, v80, v81
	v_cvt_pk_bf16_f32 v81, v82, v83
	ds_write_b64 v179, v[80:81] offset:17152
	v_cvt_pk_bf16_f32 v84, v84, v85
	v_cvt_pk_bf16_f32 v85, v86, v87
	ds_write_b64 v179, v[84:85] offset:17184
	v_cvt_pk_bf16_f32 v72, v72, v73
	v_cvt_pk_bf16_f32 v73, v74, v75
	ds_write_b64 v179, v[72:73] offset:25344
	v_cvt_pk_bf16_f32 v76, v76, v77
	v_cvt_pk_bf16_f32 v77, v78, v79
	ds_write_b64 v179, v[76:77] offset:25376
	v_cvt_pk_bf16_f32 v64, v64, v65
	v_cvt_pk_bf16_f32 v65, v66, v67
	ds_write_b64 v179, v[64:65] offset:25600
	v_cvt_pk_bf16_f32 v68, v68, v69
	v_cvt_pk_bf16_f32 v69, v70, v71
	ds_write_b64 v179, v[68:69] offset:25632
	v_cvt_pk_bf16_f32 v56, v56, v57
	v_cvt_pk_bf16_f32 v57, v58, v59
	ds_write_b64 v180, v[56:57]
	v_cvt_pk_bf16_f32 v60, v60, v61
	v_cvt_pk_bf16_f32 v61, v62, v63
	ds_write_b64 v180, v[60:61] offset:32
	v_cvt_pk_bf16_f32 v48, v48, v49
	v_cvt_pk_bf16_f32 v49, v50, v51
	ds_write_b64 v180, v[48:49] offset:256
	v_cvt_pk_bf16_f32 v52, v52, v53
	v_cvt_pk_bf16_f32 v53, v54, v55
	ds_write_b64 v180, v[52:53] offset:288
	v_cvt_pk_bf16_f32 v40, v40, v41
	v_cvt_pk_bf16_f32 v41, v42, v43
	ds_write_b64 v180, v[40:41] offset:8448
	v_cvt_pk_bf16_f32 v44, v44, v45
	v_cvt_pk_bf16_f32 v45, v46, v47
	ds_write_b64 v180, v[44:45] offset:8480
	v_cvt_pk_bf16_f32 v32, v32, v33
	v_cvt_pk_bf16_f32 v33, v34, v35
	ds_write_b64 v180, v[32:33] offset:8704
	v_cvt_pk_bf16_f32 v36, v36, v37
	v_cvt_pk_bf16_f32 v37, v38, v39
	ds_write_b64 v180, v[36:37] offset:8736
	v_cvt_pk_bf16_f32 v24, v24, v25
	v_cvt_pk_bf16_f32 v25, v26, v27
	ds_write_b64 v180, v[24:25] offset:16896
	v_cvt_pk_bf16_f32 v28, v28, v29
	v_cvt_pk_bf16_f32 v29, v30, v31
	ds_write_b64 v180, v[28:29] offset:16928
	v_cvt_pk_bf16_f32 v16, v16, v17
	v_cvt_pk_bf16_f32 v17, v18, v19
	ds_write_b64 v180, v[16:17] offset:17152
	v_cvt_pk_bf16_f32 v20, v20, v21
	v_cvt_pk_bf16_f32 v21, v22, v23
	ds_write_b64 v180, v[20:21] offset:17184
	v_cvt_pk_bf16_f32 v8, v8, v9
	v_cvt_pk_bf16_f32 v9, v10, v11
	ds_write_b64 v180, v[8:9] offset:25344
	v_cvt_pk_bf16_f32 v12, v12, v13
	v_cvt_pk_bf16_f32 v13, v14, v15
	ds_write_b64 v180, v[12:13] offset:25376
	v_cvt_pk_bf16_f32 v0, v0, v1
	v_cvt_pk_bf16_f32 v1, v2, v3
	ds_write_b64 v180, v[0:1] offset:25600
	v_cvt_pk_bf16_f32 v4, v4, v5
	v_cvt_pk_bf16_f32 v5, v6, v7
	ds_write_b64 v180, v[4:5] offset:25632
	s_branch .Lg1_readback
; template <int EPI>
; __device__ void gemm8_phase(const Params& p, const u16* __restrict__ A, const u16* __restrict__ Bt, const int K, const int nN,
;                             unsigned char* smem, const int rep) {
;     ...
;         if (EPI == 0 && bcol < 2048) {
;           const float2* rope = (const float2*)(p.ws + OFF_ROPE);
; #pragma unroll
;           for (int bj = 0; bj < 2; ++bj) {
;             __builtin_amdgcn_sched_barrier(0);
;             const int pc = bcol + bj * HALF + wc * 32;
;             const int i = ((pc & 255) >> 5) * 16 + fr;
;             const int f1 = (pc & ~255) + i;
;             float2 csv[4];
; #pragma unroll
;             for (int j = 0; j < 4; ++j) {
;               const int row = brow + ai * HALF + wr * 64 + m * 16 + fq * 4 + j;
;               const int pi = row < NPROMPT ? (row & 2047) : 2048 + ((row - NPROMPT) & 7);
;               csv[j] = rope[pi * 128 + i];
;             }
; #pragma unroll
;             for (int j = 0; j < 4; ++j) {
;               const int row = brow + ai * HALF + wr * 64 + m * 16 + fq * 4 + j;
;               u16* proj = projb + (size_t)row * PROJ_LD;
;               const float2 cs = csv[j];
;               const float x1 = acc[ai][bj][m][0][j], x2 = acc[ai][bj][m][1][j];
;               float y1 = x1 * cs.x - x2 * cs.y, y2 = x1 * cs.y + x2 * cs.x;
;               if (pc >= 1024) { y1 *= 0.0625f; y2 *= 0.0625f; }
;               proj[f1] = f2bf(y1);
;               proj[f1 + 128] = f2bf(y2);
;             }
;           }
.Lg1_rope:
	s_cmp_ge_u32 s33, 0x800
	s_cselect_b32 s1, 0x3d800000, 1.0
	s_add_i32 s7, s4, s6
	v_add_u32_e32 v181, s7, v176
	s_cmp_lt_u32 s4, 0x4000
	s_cselect_b32 s6, 0x7ff, 7
	s_cselect_b32 s7, 0, 0x800
	s_cselect_b32 s0, 0x4000, 0
	v_and_b32_e32 v182, s6, v181
	v_add_u32_e32 v182, s7, v182
	v_lshlrev_b32_e32 v182, 10, v182
	s_lshl_b32 s6, s5, 7
	v_lshl_add_u32 v182, v177, 5, v182
	v_add_u32_e32 v182, s6, v182
	s_lshl_b32 s6, s5, 5
	v_add_u32_e32 v179, s6, v179
	v_add_u32_e32 v180, 0x10800, v179
	s_mul_i32 s5, s0, 5
	global_load_dwordx4 v[196:199], v182, s[20:21]
	global_load_dwordx4 v[200:203], v182, s[20:21] offset:16
	global_load_dwordx4 v[204:207], v182, s[20:21] offset:512
	global_load_dwordx4 v[208:211], v182, s[20:21] offset:528
	v_add_u32_e32 v182, s0, v182
	global_load_dwordx4 v[212:215], v182, s[20:21]
	global_load_dwordx4 v[216:219], v182, s[20:21] offset:16
	global_load_dwordx4 v[220:223], v182, s[20:21] offset:512
	global_load_dwordx4 v[224:227], v182, s[20:21] offset:528
	v_add_u32_e32 v182, s0, v182
	global_load_dwordx4 v[228:231], v182, s[20:21]
	global_load_dwordx4 v[232:235], v182, s[20:21] offset:16
	global_load_dwordx4 v[236:239], v182, s[20:21] offset:512
	global_load_dwordx4 v[240:243], v182, s[20:21] offset:528
	v_add_u32_e32 v182, s0, v182
	s_waitcnt vmcnt(8)
	v_mul_f32_e32 v244, v124, v197
	v_mul_f32_e32 v245, v120, v197
	v_fma_f32 v120, v120, v196, -v244
	v_fmac_f32_e32 v245, v124, v196
	v_mul_f32_e32 v120, s1, v120
	v_mul_f32_e32 v124, s1, v245
	v_mul_f32_e32 v244, v125, v199
	v_mul_f32_e32 v245, v121, v199
	v_fma_f32 v121, v121, v198, -v244
	v_fmac_f32_e32 v245, v125, v198
	v_mul_f32_e32 v121, s1, v121
	v_mul_f32_e32 v125, s1, v245
	v_mul_f32_e32 v244, v126, v201
	v_mul_f32_e32 v245, v122, v201
	v_fma_f32 v122, v122, v200, -v244
	v_fmac_f32_e32 v245, v126, v200
	v_mul_f32_e32 v122, s1, v122
	v_mul_f32_e32 v126, s1, v245
	v_mul_f32_e32 v244, v127, v203
	v_mul_f32_e32 v245, v123, v203
	v_fma_f32 v123, v123, v202, -v244
	v_fmac_f32_e32 v245, v127, v202
	v_mul_f32_e32 v123, s1, v123
	v_mul_f32_e32 v127, s1, v245
	v_cvt_pk_bf16_f32 v120, v120, v121
	v_cvt_pk_bf16_f32 v121, v122, v123
	ds_write_b64 v179, v[120:121]
	v_cvt_pk_bf16_f32 v124, v124, v125
	v_cvt_pk_bf16_f32 v125, v126, v127
	ds_write_b64 v179, v[124:125] offset:256
	v_mul_f32_e32 v244, v116, v205
	v_mul_f32_e32 v245, v112, v205
	v_fma_f32 v112, v112, v204, -v244
	v_fmac_f32_e32 v245, v116, v204
	v_mul_f32_e32 v112, s1, v112
	v_mul_f32_e32 v116, s1, v245
	v_mul_f32_e32 v244, v117, v207
	v_mul_f32_e32 v245, v113, v207
	v_fma_f32 v113, v113, v206, -v244
	v_fmac_f32_e32 v245, v117, v206
	v_mul_f32_e32 v113, s1, v113
	v_mul_f32_e32 v117, s1, v245
	v_mul_f32_e32 v244, v118, v209
	v_mul_f32_e32 v245, v114, v209
	v_fma_f32 v114, v114, v208, -v244
	v_fmac_f32_e32 v245, v118, v208
	v_mul_f32_e32 v114, s1, v114
	v_mul_f32_e32 v118, s1, v245
	v_mul_f32_e32 v244, v119, v211
	v_mul_f32_e32 v245, v115, v211
	v_fma_f32 v115, v115, v210, -v244
	v_fmac_f32_e32 v245, v119, v210
	v_mul_f32_e32 v115, s1, v115
	v_mul_f32_e32 v119, s1, v245
	v_cvt_pk_bf16_f32 v112, v112, v113
	v_cvt_pk_bf16_f32 v113, v114, v115
	ds_write_b64 v179, v[112:113] offset:128
	v_cvt_pk_bf16_f32 v116, v116, v117
	v_cvt_pk_bf16_f32 v117, v118, v119
	ds_write_b64 v179, v[116:117] offset:384
	global_load_dwordx4 v[196:199], v182, s[20:21]
	global_load_dwordx4 v[200:203], v182, s[20:21] offset:16
	global_load_dwordx4 v[204:207], v182, s[20:21] offset:512
	global_load_dwordx4 v[208:211], v182, s[20:21] offset:528
	v_add_u32_e32 v182, s5, v182
	s_waitcnt vmcnt(8)
	v_mul_f32_e32 v244, v108, v213
	v_mul_f32_e32 v245, v104, v213
	v_fma_f32 v104, v104, v212, -v244
	v_fmac_f32_e32 v245, v108, v212
	v_mul_f32_e32 v104, s1, v104
	v_mul_f32_e32 v108, s1, v245
	v_mul_f32_e32 v244, v109, v215
	v_mul_f32_e32 v245, v105, v215
	v_fma_f32 v105, v105, v214, -v244
	v_fmac_f32_e32 v245, v109, v214
	v_mul_f32_e32 v105, s1, v105
	v_mul_f32_e32 v109, s1, v245
	v_mul_f32_e32 v244, v110, v217
	v_mul_f32_e32 v245, v106, v217
	v_fma_f32 v106, v106, v216, -v244
	v_fmac_f32_e32 v245, v110, v216
	v_mul_f32_e32 v106, s1, v106
	v_mul_f32_e32 v110, s1, v245
	v_mul_f32_e32 v244, v111, v219
	v_mul_f32_e32 v245, v107, v219
	v_fma_f32 v107, v107, v218, -v244
	v_fmac_f32_e32 v245, v111, v218
	v_mul_f32_e32 v107, s1, v107
	v_mul_f32_e32 v111, s1, v245
	v_cvt_pk_bf16_f32 v104, v104, v105
	v_cvt_pk_bf16_f32 v105, v106, v107
	ds_write_b64 v179, v[104:105] offset:8448
	v_cvt_pk_bf16_f32 v108, v108, v109
	v_cvt_pk_bf16_f32 v109, v110, v111
	ds_write_b64 v179, v[108:109] offset:8704
	v_mul_f32_e32 v244, v100, v221
	v_mul_f32_e32 v245, v96, v221
	v_fma_f32 v96, v96, v220, -v244
	v_fmac_f32_e32 v245, v100, v220
	v_mul_f32_e32 v96, s1, v96
	v_mul_f32_e32 v100, s1, v245
	v_mul_f32_e32 v244, v101, v223
	v_mul_f32_e32 v245, v97, v223
	v_fma_f32 v97, v97, v222, -v244
	v_fmac_f32_e32 v245, v101, v222
	v_mul_f32_e32 v97, s1, v97
	v_mul_f32_e32 v101, s1, v245
	v_mul_f32_e32 v244, v102, v225
	v_mul_f32_e32 v245, v98, v225
	v_fma_f32 v98, v98, v224, -v244
	v_fmac_f32_e32 v245, v102, v224
	v_mul_f32_e32 v98, s1, v98
	v_mul_f32_e32 v102, s1, v245
	v_mul_f32_e32 v244, v103, v227
	v_mul_f32_e32 v245, v99, v227
	v_fma_f32 v99, v99, v226, -v244
	v_fmac_f32_e32 v245, v103, v226
	v_mul_f32_e32 v99, s1, v99
	v_mul_f32_e32 v103, s1, v245
	v_cvt_pk_bf16_f32 v96, v96, v97
	v_cvt_pk_bf16_f32 v97, v98, v99
	ds_write_b64 v179, v[96:97] offset:8576
	v_cvt_pk_bf16_f32 v100, v100, v101
	v_cvt_pk_bf16_f32 v101, v102, v103
	ds_write_b64 v179, v[100:101] offset:8832
	global_load_dwordx4 v[212:215], v182, s[20:21]
	global_load_dwordx4 v[216:219], v182, s[20:21] offset:16
	global_load_dwordx4 v[220:223], v182, s[20:21] offset:512
	global_load_dwordx4 v[224:227], v182, s[20:21] offset:528
	v_add_u32_e32 v182, s0, v182
	s_waitcnt vmcnt(8)
; template <int EPI>
; __device__ void gemm8_phase(const Params& p, const u16* __restrict__ A, const u16* __restrict__ Bt, const int K, const int nN,
;                             unsigned char* smem, const int rep) {
;     ...
;             for (int j = 0; j < 4; ++j) {
;               const int row = brow + ai * HALF + wr * 64 + m * 16 + fq * 4 + j;
;               const int pi = row < NPROMPT ? (row & 2047) : 2048 + ((row - NPROMPT) & 7);
;               csv[j] = rope[pi * 128 + i];
;             }
; #pragma unroll
;             for (int j = 0; j < 4; ++j) {
;               const int row = brow + ai * HALF + wr * 64 + m * 16 + fq * 4 + j;
;               u16* proj = projb + (size_t)row * PROJ_LD;
;               const float2 cs = csv[j];
;               const float x1 = acc[ai][bj][m][0][j], x2 = acc[ai][bj][m][1][j];
;               float y1 = x1 * cs.x - x2 * cs.y, y2 = x1 * cs.y + x2 * cs.x;
;               if (pc >= 1024) { y1 *= 0.0625f; y2 *= 0.0625f; }
;               proj[f1] = f2bf(y1);
;               proj[f1 + 128] = f2bf(y2);
;             }
	v_mul_f32_e32 v244, v92, v229
	v_mul_f32_e32 v245, v88, v229
	v_fma_f32 v88, v88, v228, -v244
	v_fmac_f32_e32 v245, v92, v228
	v_mul_f32_e32 v88, s1, v88
	v_mul_f32_e32 v92, s1, v245
	v_mul_f32_e32 v244, v93, v231
	v_mul_f32_e32 v245, v89, v231
	v_fma_f32 v89, v89, v230, -v244
	v_fmac_f32_e32 v245, v93, v230
	v_mul_f32_e32 v89, s1, v89
	v_mul_f32_e32 v93, s1, v245
	v_mul_f32_e32 v244, v94, v233
	v_mul_f32_e32 v245, v90, v233
	v_fma_f32 v90, v90, v232, -v244
	v_fmac_f32_e32 v245, v94, v232
	v_mul_f32_e32 v90, s1, v90
	v_mul_f32_e32 v94, s1, v245
	v_mul_f32_e32 v244, v95, v235
	v_mul_f32_e32 v245, v91, v235
	v_fma_f32 v91, v91, v234, -v244
	v_fmac_f32_e32 v245, v95, v234
	v_mul_f32_e32 v91, s1, v91
	v_mul_f32_e32 v95, s1, v245
	v_cvt_pk_bf16_f32 v88, v88, v89
	v_cvt_pk_bf16_f32 v89, v90, v91
	ds_write_b64 v179, v[88:89] offset:16896
	v_cvt_pk_bf16_f32 v92, v92, v93
	v_cvt_pk_bf16_f32 v93, v94, v95
	ds_write_b64 v179, v[92:93] offset:17152
	v_mul_f32_e32 v244, v84, v237
	v_mul_f32_e32 v245, v80, v237
	v_fma_f32 v80, v80, v236, -v244
	v_fmac_f32_e32 v245, v84, v236
	v_mul_f32_e32 v80, s1, v80
	v_mul_f32_e32 v84, s1, v245
	v_mul_f32_e32 v244, v85, v239
	v_mul_f32_e32 v245, v81, v239
	v_fma_f32 v81, v81, v238, -v244
	v_fmac_f32_e32 v245, v85, v238
	v_mul_f32_e32 v81, s1, v81
	v_mul_f32_e32 v85, s1, v245
	v_mul_f32_e32 v244, v86, v241
	v_mul_f32_e32 v245, v82, v241
	v_fma_f32 v82, v82, v240, -v244
	v_fmac_f32_e32 v245, v86, v240
	v_mul_f32_e32 v82, s1, v82
	v_mul_f32_e32 v86, s1, v245
	v_mul_f32_e32 v244, v87, v243
	v_mul_f32_e32 v245, v83, v243
	v_fma_f32 v83, v83, v242, -v244
	v_fmac_f32_e32 v245, v87, v242
	v_mul_f32_e32 v83, s1, v83
	v_mul_f32_e32 v87, s1, v245
	v_cvt_pk_bf16_f32 v80, v80, v81
	v_cvt_pk_bf16_f32 v81, v82, v83
	ds_write_b64 v179, v[80:81] offset:17024
	v_cvt_pk_bf16_f32 v84, v84, v85
	v_cvt_pk_bf16_f32 v85, v86, v87
	ds_write_b64 v179, v[84:85] offset:17280
	global_load_dwordx4 v[228:231], v182, s[20:21]
	global_load_dwordx4 v[232:235], v182, s[20:21] offset:16
	global_load_dwordx4 v[236:239], v182, s[20:21] offset:512
	global_load_dwordx4 v[240:243], v182, s[20:21] offset:528
	v_add_u32_e32 v182, s0, v182
	s_waitcnt vmcnt(8)
	v_mul_f32_e32 v244, v76, v197
	v_mul_f32_e32 v245, v72, v197
	v_fma_f32 v72, v72, v196, -v244
	v_fmac_f32_e32 v245, v76, v196
	v_mul_f32_e32 v72, s1, v72
	v_mul_f32_e32 v76, s1, v245
	v_mul_f32_e32 v244, v77, v199
	v_mul_f32_e32 v245, v73, v199
	v_fma_f32 v73, v73, v198, -v244
	v_fmac_f32_e32 v245, v77, v198
	v_mul_f32_e32 v73, s1, v73
	v_mul_f32_e32 v77, s1, v245
	v_mul_f32_e32 v244, v78, v201
	v_mul_f32_e32 v245, v74, v201
	v_fma_f32 v74, v74, v200, -v244
	v_fmac_f32_e32 v245, v78, v200
	v_mul_f32_e32 v74, s1, v74
	v_mul_f32_e32 v78, s1, v245
	v_mul_f32_e32 v244, v79, v203
	v_mul_f32_e32 v245, v75, v203
	v_fma_f32 v75, v75, v202, -v244
	v_fmac_f32_e32 v245, v79, v202
	v_mul_f32_e32 v75, s1, v75
	v_mul_f32_e32 v79, s1, v245
	v_cvt_pk_bf16_f32 v72, v72, v73
	v_cvt_pk_bf16_f32 v73, v74, v75
	ds_write_b64 v179, v[72:73] offset:25344
	v_cvt_pk_bf16_f32 v76, v76, v77
	v_cvt_pk_bf16_f32 v77, v78, v79
	ds_write_b64 v179, v[76:77] offset:25600
	v_mul_f32_e32 v244, v68, v205
	v_mul_f32_e32 v245, v64, v205
	v_fma_f32 v64, v64, v204, -v244
	v_fmac_f32_e32 v245, v68, v204
	v_mul_f32_e32 v64, s1, v64
	v_mul_f32_e32 v68, s1, v245
	v_mul_f32_e32 v244, v69, v207
	v_mul_f32_e32 v245, v65, v207
	v_fma_f32 v65, v65, v206, -v244
	v_fmac_f32_e32 v245, v69, v206
	v_mul_f32_e32 v65, s1, v65
	v_mul_f32_e32 v69, s1, v245
	v_mul_f32_e32 v244, v70, v209
	v_mul_f32_e32 v245, v66, v209
	v_fma_f32 v66, v66, v208, -v244
	v_fmac_f32_e32 v245, v70, v208
	v_mul_f32_e32 v66, s1, v66
	v_mul_f32_e32 v70, s1, v245
	v_mul_f32_e32 v244, v71, v211
	v_mul_f32_e32 v245, v67, v211
	v_fma_f32 v67, v67, v210, -v244
	v_fmac_f32_e32 v245, v71, v210
	v_mul_f32_e32 v67, s1, v67
	v_mul_f32_e32 v71, s1, v245
	v_cvt_pk_bf16_f32 v64, v64, v65
	v_cvt_pk_bf16_f32 v65, v66, v67
	ds_write_b64 v179, v[64:65] offset:25472
	v_cvt_pk_bf16_f32 v68, v68, v69
	v_cvt_pk_bf16_f32 v69, v70, v71
	ds_write_b64 v179, v[68:69] offset:25728
	global_load_dwordx4 v[196:199], v182, s[20:21]
	global_load_dwordx4 v[200:203], v182, s[20:21] offset:16
	global_load_dwordx4 v[204:207], v182, s[20:21] offset:512
	global_load_dwordx4 v[208:211], v182, s[20:21] offset:528
	v_add_u32_e32 v182, s0, v182
	s_waitcnt vmcnt(8)
	v_mul_f32_e32 v244, v60, v213
	v_mul_f32_e32 v245, v56, v213
	v_fma_f32 v56, v56, v212, -v244
	v_fmac_f32_e32 v245, v60, v212
	v_mul_f32_e32 v56, s1, v56
	v_mul_f32_e32 v60, s1, v245
	v_mul_f32_e32 v244, v61, v215
	v_mul_f32_e32 v245, v57, v215
	v_fma_f32 v57, v57, v214, -v244
	v_fmac_f32_e32 v245, v61, v214
	v_mul_f32_e32 v57, s1, v57
	v_mul_f32_e32 v61, s1, v245
	v_mul_f32_e32 v244, v62, v217
	v_mul_f32_e32 v245, v58, v217
	v_fma_f32 v58, v58, v216, -v244
	v_fmac_f32_e32 v245, v62, v216
	v_mul_f32_e32 v58, s1, v58
	v_mul_f32_e32 v62, s1, v245
	v_mul_f32_e32 v244, v63, v219
	v_mul_f32_e32 v245, v59, v219
	v_fma_f32 v59, v59, v218, -v244
	v_fmac_f32_e32 v245, v63, v218
	v_mul_f32_e32 v59, s1, v59
	v_mul_f32_e32 v63, s1, v245
	v_cvt_pk_bf16_f32 v56, v56, v57
	v_cvt_pk_bf16_f32 v57, v58, v59
	ds_write_b64 v180, v[56:57]
	v_cvt_pk_bf16_f32 v60, v60, v61
	v_cvt_pk_bf16_f32 v61, v62, v63
	ds_write_b64 v180, v[60:61] offset:256
	v_mul_f32_e32 v244, v52, v221
	v_mul_f32_e32 v245, v48, v221
	v_fma_f32 v48, v48, v220, -v244
	v_fmac_f32_e32 v245, v52, v220
	v_mul_f32_e32 v48, s1, v48
	v_mul_f32_e32 v52, s1, v245
	v_mul_f32_e32 v244, v53, v223
	v_mul_f32_e32 v245, v49, v223
	v_fma_f32 v49, v49, v222, -v244
	v_fmac_f32_e32 v245, v53, v222
	v_mul_f32_e32 v49, s1, v49
	v_mul_f32_e32 v53, s1, v245
	v_mul_f32_e32 v244, v54, v225
	v_mul_f32_e32 v245, v50, v225
	v_fma_f32 v50, v50, v224, -v244
	v_fmac_f32_e32 v245, v54, v224
	v_mul_f32_e32 v50, s1, v50
	v_mul_f32_e32 v54, s1, v245
	v_mul_f32_e32 v244, v55, v227
	v_mul_f32_e32 v245, v51, v227
	v_fma_f32 v51, v51, v226, -v244
	v_fmac_f32_e32 v245, v55, v226
	v_mul_f32_e32 v51, s1, v51
	v_mul_f32_e32 v55, s1, v245
	v_cvt_pk_bf16_f32 v48, v48, v49
	v_cvt_pk_bf16_f32 v49, v50, v51
	ds_write_b64 v180, v[48:49] offset:128
	v_cvt_pk_bf16_f32 v52, v52, v53
	v_cvt_pk_bf16_f32 v53, v54, v55
	ds_write_b64 v180, v[52:53] offset:384
	global_load_dwordx4 v[212:215], v182, s[20:21]
	global_load_dwordx4 v[216:219], v182, s[20:21] offset:16
	global_load_dwordx4 v[220:223], v182, s[20:21] offset:512
	global_load_dwordx4 v[224:227], v182, s[20:21] offset:528
	s_waitcnt vmcnt(8)
; template <int EPI>
; __device__ void gemm8_phase(const Params& p, const u16* __restrict__ A, const u16* __restrict__ Bt, const int K, const int nN,
;                             unsigned char* smem, const int rep) {
;     ...
;             for (int j = 0; j < 4; ++j) {
;               const int row = brow + ai * HALF + wr * 64 + m * 16 + fq * 4 + j;
;               const int pi = row < NPROMPT ? (row & 2047) : 2048 + ((row - NPROMPT) & 7);
;               csv[j] = rope[pi * 128 + i];
;             }
; #pragma unroll
;             for (int j = 0; j < 4; ++j) {
;               const int row = brow + ai * HALF + wr * 64 + m * 16 + fq * 4 + j;
;               u16* proj = projb + (size_t)row * PROJ_LD;
;               const float2 cs = csv[j];
;               const float x1 = acc[ai][bj][m][0][j], x2 = acc[ai][bj][m][1][j];
;               float y1 = x1 * cs.x - x2 * cs.y, y2 = x1 * cs.y + x2 * cs.x;
;               if (pc >= 1024) { y1 *= 0.0625f; y2 *= 0.0625f; }
;               proj[f1] = f2bf(y1);
;               proj[f1 + 128] = f2bf(y2);
;             }
	v_mul_f32_e32 v244, v44, v229
	v_mul_f32_e32 v245, v40, v229
	v_fma_f32 v40, v40, v228, -v244
	v_fmac_f32_e32 v245, v44, v228
	v_mul_f32_e32 v40, s1, v40
	v_mul_f32_e32 v44, s1, v245
	v_mul_f32_e32 v244, v45, v231
	v_mul_f32_e32 v245, v41, v231
	v_fma_f32 v41, v41, v230, -v244
	v_fmac_f32_e32 v245, v45, v230
	v_mul_f32_e32 v41, s1, v41
	v_mul_f32_e32 v45, s1, v245
	v_mul_f32_e32 v244, v46, v233
	v_mul_f32_e32 v245, v42, v233
	v_fma_f32 v42, v42, v232, -v244
	v_fmac_f32_e32 v245, v46, v232
	v_mul_f32_e32 v42, s1, v42
	v_mul_f32_e32 v46, s1, v245
	v_mul_f32_e32 v244, v47, v235
	v_mul_f32_e32 v245, v43, v235
	v_fma_f32 v43, v43, v234, -v244
	v_fmac_f32_e32 v245, v47, v234
	v_mul_f32_e32 v43, s1, v43
	v_mul_f32_e32 v47, s1, v245
	v_cvt_pk_bf16_f32 v40, v40, v41
	v_cvt_pk_bf16_f32 v41, v42, v43
	ds_write_b64 v180, v[40:41] offset:8448
	v_cvt_pk_bf16_f32 v44, v44, v45
	v_cvt_pk_bf16_f32 v45, v46, v47
	ds_write_b64 v180, v[44:45] offset:8704
	v_mul_f32_e32 v244, v36, v237
	v_mul_f32_e32 v245, v32, v237
	v_fma_f32 v32, v32, v236, -v244
	v_fmac_f32_e32 v245, v36, v236
	v_mul_f32_e32 v32, s1, v32
	v_mul_f32_e32 v36, s1, v245
	v_mul_f32_e32 v244, v37, v239
	v_mul_f32_e32 v245, v33, v239
	v_fma_f32 v33, v33, v238, -v244
	v_fmac_f32_e32 v245, v37, v238
	v_mul_f32_e32 v33, s1, v33
	v_mul_f32_e32 v37, s1, v245
	v_mul_f32_e32 v244, v38, v241
	v_mul_f32_e32 v245, v34, v241
	v_fma_f32 v34, v34, v240, -v244
	v_fmac_f32_e32 v245, v38, v240
	v_mul_f32_e32 v34, s1, v34
	v_mul_f32_e32 v38, s1, v245
	v_mul_f32_e32 v244, v39, v243
	v_mul_f32_e32 v245, v35, v243
	v_fma_f32 v35, v35, v242, -v244
	v_fmac_f32_e32 v245, v39, v242
	v_mul_f32_e32 v35, s1, v35
	v_mul_f32_e32 v39, s1, v245
	v_cvt_pk_bf16_f32 v32, v32, v33
	v_cvt_pk_bf16_f32 v33, v34, v35
	ds_write_b64 v180, v[32:33] offset:8576
	v_cvt_pk_bf16_f32 v36, v36, v37
	v_cvt_pk_bf16_f32 v37, v38, v39
	ds_write_b64 v180, v[36:37] offset:8832
	s_waitcnt vmcnt(4)
	v_mul_f32_e32 v244, v28, v197
	v_mul_f32_e32 v245, v24, v197
	v_fma_f32 v24, v24, v196, -v244
	v_fmac_f32_e32 v245, v28, v196
	v_mul_f32_e32 v24, s1, v24
	v_mul_f32_e32 v28, s1, v245
	v_mul_f32_e32 v244, v29, v199
	v_mul_f32_e32 v245, v25, v199
	v_fma_f32 v25, v25, v198, -v244
	v_fmac_f32_e32 v245, v29, v198
	v_mul_f32_e32 v25, s1, v25
	v_mul_f32_e32 v29, s1, v245
	v_mul_f32_e32 v244, v30, v201
	v_mul_f32_e32 v245, v26, v201
	v_fma_f32 v26, v26, v200, -v244
	v_fmac_f32_e32 v245, v30, v200
	v_mul_f32_e32 v26, s1, v26
	v_mul_f32_e32 v30, s1, v245
	v_mul_f32_e32 v244, v31, v203
	v_mul_f32_e32 v245, v27, v203
	v_fma_f32 v27, v27, v202, -v244
	v_fmac_f32_e32 v245, v31, v202
	v_mul_f32_e32 v27, s1, v27
	v_mul_f32_e32 v31, s1, v245
	v_cvt_pk_bf16_f32 v24, v24, v25
	v_cvt_pk_bf16_f32 v25, v26, v27
	ds_write_b64 v180, v[24:25] offset:16896
	v_cvt_pk_bf16_f32 v28, v28, v29
	v_cvt_pk_bf16_f32 v29, v30, v31
	ds_write_b64 v180, v[28:29] offset:17152
	v_mul_f32_e32 v244, v20, v205
	v_mul_f32_e32 v245, v16, v205
	v_fma_f32 v16, v16, v204, -v244
	v_fmac_f32_e32 v245, v20, v204
	v_mul_f32_e32 v16, s1, v16
	v_mul_f32_e32 v20, s1, v245
	v_mul_f32_e32 v244, v21, v207
	v_mul_f32_e32 v245, v17, v207
	v_fma_f32 v17, v17, v206, -v244
	v_fmac_f32_e32 v245, v21, v206
	v_mul_f32_e32 v17, s1, v17
	v_mul_f32_e32 v21, s1, v245
	v_mul_f32_e32 v244, v22, v209
	v_mul_f32_e32 v245, v18, v209
	v_fma_f32 v18, v18, v208, -v244
	v_fmac_f32_e32 v245, v22, v208
	v_mul_f32_e32 v18, s1, v18
	v_mul_f32_e32 v22, s1, v245
	v_mul_f32_e32 v244, v23, v211
	v_mul_f32_e32 v245, v19, v211
	v_fma_f32 v19, v19, v210, -v244
	v_fmac_f32_e32 v245, v23, v210
	v_mul_f32_e32 v19, s1, v19
	v_mul_f32_e32 v23, s1, v245
	v_cvt_pk_bf16_f32 v16, v16, v17
	v_cvt_pk_bf16_f32 v17, v18, v19
	ds_write_b64 v180, v[16:17] offset:17024
	v_cvt_pk_bf16_f32 v20, v20, v21
	v_cvt_pk_bf16_f32 v21, v22, v23
	ds_write_b64 v180, v[20:21] offset:17280
	s_waitcnt vmcnt(0)
	v_mul_f32_e32 v244, v12, v213
	v_mul_f32_e32 v245, v8, v213
	v_fma_f32 v8, v8, v212, -v244
	v_fmac_f32_e32 v245, v12, v212
	v_mul_f32_e32 v8, s1, v8
	v_mul_f32_e32 v12, s1, v245
	v_mul_f32_e32 v244, v13, v215
	v_mul_f32_e32 v245, v9, v215
	v_fma_f32 v9, v9, v214, -v244
	v_fmac_f32_e32 v245, v13, v214
	v_mul_f32_e32 v9, s1, v9
	v_mul_f32_e32 v13, s1, v245
	v_mul_f32_e32 v244, v14, v217
	v_mul_f32_e32 v245, v10, v217
	v_fma_f32 v10, v10, v216, -v244
	v_fmac_f32_e32 v245, v14, v216
	v_mul_f32_e32 v10, s1, v10
	v_mul_f32_e32 v14, s1, v245
	v_mul_f32_e32 v244, v15, v219
	v_mul_f32_e32 v245, v11, v219
	v_fma_f32 v11, v11, v218, -v244
	v_fmac_f32_e32 v245, v15, v218
	v_mul_f32_e32 v11, s1, v11
	v_mul_f32_e32 v15, s1, v245
	v_cvt_pk_bf16_f32 v8, v8, v9
	v_cvt_pk_bf16_f32 v9, v10, v11
	ds_write_b64 v180, v[8:9] offset:25344
	v_cvt_pk_bf16_f32 v12, v12, v13
	v_cvt_pk_bf16_f32 v13, v14, v15
	ds_write_b64 v180, v[12:13] offset:25600
	v_mul_f32_e32 v244, v4, v221
	v_mul_f32_e32 v245, v0, v221
	v_fma_f32 v0, v0, v220, -v244
	v_fmac_f32_e32 v245, v4, v220
	v_mul_f32_e32 v0, s1, v0
	v_mul_f32_e32 v4, s1, v245
	v_mul_f32_e32 v244, v5, v223
	v_mul_f32_e32 v245, v1, v223
	v_fma_f32 v1, v1, v222, -v244
	v_fmac_f32_e32 v245, v5, v222
	v_mul_f32_e32 v1, s1, v1
	v_mul_f32_e32 v5, s1, v245
	v_mul_f32_e32 v244, v6, v225
	v_mul_f32_e32 v245, v2, v225
	v_fma_f32 v2, v2, v224, -v244
	v_fmac_f32_e32 v245, v6, v224
	v_mul_f32_e32 v2, s1, v2
	v_mul_f32_e32 v6, s1, v245
	v_mul_f32_e32 v244, v7, v227
	v_mul_f32_e32 v245, v3, v227
	v_fma_f32 v3, v3, v226, -v244
	v_fmac_f32_e32 v245, v7, v226
	v_mul_f32_e32 v3, s1, v3
	v_mul_f32_e32 v7, s1, v245
	v_cvt_pk_bf16_f32 v0, v0, v1
	v_cvt_pk_bf16_f32 v1, v2, v3
	ds_write_b64 v180, v[0:1] offset:25472
	v_cvt_pk_bf16_f32 v4, v4, v5
	v_cvt_pk_bf16_f32 v5, v6, v7
	ds_write_b64 v180, v[4:5] offset:25728
; template <int EPI>
; __device__ void gemm8_phase(const Params& p, const u16* __restrict__ A, const u16* __restrict__ Bt, const int K, const int nN,
;                             unsigned char* smem, const int rep) {
;     ...
;               u16* proj = projb + (size_t)row * PROJ_LD;
;               const float2 cs = csv[j];
;               const float x1 = acc[ai][bj][m][0][j], x2 = acc[ai][bj][m][1][j];
;               float y1 = x1 * cs.x - x2 * cs.y, y2 = x1 * cs.y + x2 * cs.x;
;               if (pc >= 1024) { y1 *= 0.0625f; y2 *= 0.0625f; }
;               proj[f1] = f2bf(y1);
;               proj[f1 + 128] = f2bf(y2);
;     ...
;                 const int col = bcol + bj * HALF + wc * 32 + n * 16 + fr;
;                 const float a = acc[ai][bj][m][n][j];
;                 proj[col] = f2bf(a);
.Lg1_readback:
	s_waitcnt lgkmcnt(0)
	s_barrier
	v_readlane_b32 s7, v255, 6
	v_lshrrev_b32_e32 v178, 5, v195
	v_and_b32_e32 v176, 31, v195
	s_lshl_b32 s7, s7, 5
	v_add_u32_e32 v178, s7, v178
	v_lshlrev_b32_e32 v176, 4, v176
	v_add_u32_e32 v177, s4, v178
	v_mul_u32_u24_e32 v177, 0x3080, v177
	v_mul_u32_u24_e32 v178, 0x210, v178
	v_add3_u32 v177, v177, v176, s33
	v_add_u32_e32 v176, v178, v176
	ds_read_b128 v[0:3], v176
	ds_read_b128 v[4:7], v176 offset:1056
	ds_read_b128 v[8:11], v176 offset:2112
	ds_read_b128 v[12:15], v176 offset:3168
	ds_read_b128 v[16:19], v176 offset:4224
	ds_read_b128 v[20:23], v176 offset:5280
	ds_read_b128 v[24:27], v176 offset:6336
	ds_read_b128 v[28:31], v176 offset:7392
	ds_read_b128 v[32:35], v176 offset:8448
	ds_read_b128 v[36:39], v176 offset:9504
	ds_read_b128 v[40:43], v176 offset:10560
	ds_read_b128 v[44:47], v176 offset:11616
	ds_read_b128 v[48:51], v176 offset:12672
	ds_read_b128 v[52:55], v176 offset:13728
	ds_read_b128 v[56:59], v176 offset:14784
	ds_read_b128 v[60:63], v176 offset:15840
	s_waitcnt lgkmcnt(15)
	global_store_dwordx4 v177, v[0:3], s[18:19]
	v_add_u32_e32 v177, 0x6100, v177
	s_waitcnt lgkmcnt(14)
	global_store_dwordx4 v177, v[4:7], s[18:19]
	v_add_u32_e32 v177, 0x6100, v177
	s_waitcnt lgkmcnt(13)
	global_store_dwordx4 v177, v[8:11], s[18:19]
	v_add_u32_e32 v177, 0x6100, v177
	s_waitcnt lgkmcnt(12)
	global_store_dwordx4 v177, v[12:15], s[18:19]
	v_add_u32_e32 v177, 0x6100, v177
	s_waitcnt lgkmcnt(11)
	global_store_dwordx4 v177, v[16:19], s[18:19]
	v_add_u32_e32 v177, 0x6100, v177
	s_waitcnt lgkmcnt(10)
	global_store_dwordx4 v177, v[20:23], s[18:19]
	v_add_u32_e32 v177, 0x6100, v177
	s_waitcnt lgkmcnt(9)
	global_store_dwordx4 v177, v[24:27], s[18:19]
	v_add_u32_e32 v177, 0x6100, v177
	s_waitcnt lgkmcnt(8)
	global_store_dwordx4 v177, v[28:31], s[18:19]
	v_add_u32_e32 v177, 0x6100, v177
	s_waitcnt lgkmcnt(7)
	global_store_dwordx4 v177, v[32:35], s[18:19]
	v_add_u32_e32 v177, 0x6100, v177
	s_waitcnt lgkmcnt(6)
	global_store_dwordx4 v177, v[36:39], s[18:19]
	v_add_u32_e32 v177, 0x6100, v177
	s_waitcnt lgkmcnt(5)
	global_store_dwordx4 v177, v[40:43], s[18:19]
	v_add_u32_e32 v177, 0x6100, v177
	s_waitcnt lgkmcnt(4)
	global_store_dwordx4 v177, v[44:47], s[18:19]
	v_add_u32_e32 v177, 0x6100, v177
	s_waitcnt lgkmcnt(3)
	global_store_dwordx4 v177, v[48:51], s[18:19]
	v_add_u32_e32 v177, 0x6100, v177
	s_waitcnt lgkmcnt(2)
	global_store_dwordx4 v177, v[52:55], s[18:19]
	v_add_u32_e32 v177, 0x6100, v177
	s_waitcnt lgkmcnt(1)
	global_store_dwordx4 v177, v[56:59], s[18:19]
	v_add_u32_e32 v177, 0x6100, v177
	s_waitcnt lgkmcnt(0)
	global_store_dwordx4 v177, v[60:63], s[18:19]
	s_barrier
	s_branch .LBB0_198

; #define WAIT_V(n) asm volatile("s_waitcnt vmcnt(" #n ")" ::: "memory")
; #define BAR __builtin_amdgcn_s_barrier()
; template <int EPI>
; __device__ void gemm8_phase(const Params& p, const u16* __restrict__ A, const u16* __restrict__ Bt, const int K, const int nN,
;                             unsigned char* smem, const int rep) {
;     ...
;   const int nM = T_TOK / BM8, nwg = nM * nN;
;   const int wid = (int)p.wv, lane = (int)p.tidx & 63, wr = wid >> 2, wc = wid & 3, fr = lane & 15, fq = lane >> 4;
;   const int nt = K / BK8;
;   const __amdgpu_buffer_rsrc_t rsrc_A = __builtin_amdgcn_make_buffer_rsrc((void*)A, (short)0, T_TOK * K * 2, 0x00020000);
;   const __amdgpu_buffer_rsrc_t rsrc_Bt = __builtin_amdgcn_make_buffer_rsrc((void*)Bt, (short)0, nN * 256 * K * 2, 0x00020000);
;   int voff0, voff1;
;   {
;     int r_, c_;
;     stage_rc((int)p.tidx * 16, r_, c_);
;     voff0 = (r_ * K + c_) * 2;
;     stage_rc((int)p.tidx * 16 + 8192, r_, c_);
;     voff1 = (r_ * K + c_) * 2;
;   }
;   for (int tile0 = blockIdx.x; tile0 < nwg * rep; tile0 += gridDim.x) {
;     const int tile = tile0 % nwg;
;     int wgid = tile;
;     {
;       int q = nwg / NXCD, r = nwg % NXCD, xcd = wgid % NXCD, off = wgid / NXCD;
;       wgid = (xcd < r ? xcd * (q + 1) : r * (q + 1) + (xcd - r) * q) + off;
;     }
;     const int nig = WGM * nN, gid = wgid / nig, fm = gid * WGM, gsz = min(nM - fm, WGM);
;     const int pm = fm + ((wgid % nig) % gsz), pn = (wgid % nig) / gsz, brow = pm * BM8, bcol = pn * BM8;
;     f32x4 acc[2][2][4][2];
; #pragma unroll
;     for (int a = 0; a < 2; ++a)
; #pragma unroll
;       for (int b = 0; b < 2; ++b)
; #pragma unroll
;         for (int m = 0; m < 4; ++m)
; #pragma unroll
;           for (int n = 0; n < 2; ++n) acc[a][b][m][n] = (f32x4){0.f, 0.f, 0.f, 0.f};
;     bf16x8 At[4][2], B0[2][2], B1[2][2];
;     STAGE(SB(0, 0), Bt, bcol, 0); STAGE(SA(0, 0), A, brow, 0);
;     STAGE(SB(0, 1), Bt, bcol + HALF, 0); STAGE(SA(0, 1), A, brow + HALF, 0);
;     if (wr == 1) BAR;
;     WAIT_V(4); BAR;
;     STAGE(SB(1, 0), Bt, bcol, 1); STAGE(SA(1, 0), A, brow, 1); STAGE(SB(1, 1), Bt, bcol + HALF, 1);
;     WAIT_V(6); BAR;
.LBB0_1054:
	s_cmp_lt_i32 s86, 6
	s_cselect_b64 s[0:1], -1, 0
	s_cmp_gt_i32 s88, 4
	s_cselect_b64 s[2:3], -1, 0
	s_and_b64 s[0:1], s[0:1], s[2:3]
	s_andn2_b64 vcc, exec, s[0:1]
	s_cbranch_vccnz .LBB0_1422
	s_mov_b64 s[0:1], 0
	s_add_u32 s16, s84, s0
	s_addc_u32 s17, s85, s1
	s_add_u32 s18, s16, 0x2242000
	s_addc_u32 s19, s17, 0
	s_add_u32 s20, s16, 0x1000000
	s_mov_b32 s3, 0
	s_waitcnt vmcnt(1)
	v_mbcnt_lo_u32_b32 v0, -1, 0
	s_addc_u32 s21, s17, 0
	s_and_b32 s2, s90, 32
	v_mbcnt_hi_u32_b32 v156, -1, v0
	s_cmp_eq_u64 s[2:3], 0
	s_movk_i32 s2, 0x660
	v_readlane_b32 s38, v255, 6
	s_cselect_b32 s39, s2, 0xcc0
	v_bfe_u32 v129, v156, 4, 2
	s_cmp_ge_i32 s78, s39
	v_lshl_add_u32 v141, s38, 6, v156
	v_and_b32_e32 v140, 15, v156
	v_lshlrev_b32_e32 v128, 4, v129
	s_cbranch_scc1 .LBB0_1220
	v_bfe_i32 v1, v141, 27, 1
	v_lshlrev_b32_e32 v142, 4, v141
	v_lshrrev_b32_e32 v1, 22, v1
	v_add_u32_e32 v1, v142, v1
	v_and_b32_e32 v1, 0xfffffc00, v1
	v_sub_u32_e32 v1, v142, v1
	v_lshrrev_b32_e32 v2, 4, v1
	v_bitop3_b32 v1, v2, v1, 32 bitop3:0x6c
	v_ashrrev_i32_e32 v0, 31, v141
	v_ashrrev_i32_e32 v3, 31, v1
	v_lshrrev_b32_e32 v0, 26, v0
	v_lshrrev_b32_e32 v3, 26, v3
	v_add_u32_e32 v0, v141, v0
	v_add_u32_e32 v3, v1, v3
	v_ashrrev_i32_e32 v0, 6, v0
	v_lshrrev_b32_e32 v4, 6, v3
	v_and_b32_e32 v3, 0xc0, v3
	v_lshlrev_b32_e32 v2, 3, v0
	v_lshlrev_b32_e32 v0, 5, v0
	v_sub_u32_e32 v1, v1, v3
	v_mov_b32_e32 v3, 1
	v_and_b32_e32 v2, 0x1ffff0, v2
	v_and_b32_e32 v0, 32, v0
	v_ashrrev_i16_sdwa v1, v3, sext(v1) dst_sel:DWORD dst_unused:UNUSED_PAD src0_sel:DWORD src1_sel:BYTE_0
	v_add_u32_sdwa v0, v0, sext(v1) dst_sel:DWORD dst_unused:UNUSED_PAD src0_sel:DWORD src1_sel:WORD_0
	v_add_lshl_u32 v1, v4, v2, 11
	v_add_u32_e32 v144, 0x2000, v142
	v_lshl_add_u32 v143, v0, 1, v1
	v_ashrrev_i32_e32 v0, 31, v144
	v_lshrrev_b32_e32 v0, 22, v0
	v_add_u32_e32 v0, v144, v0
	v_ashrrev_i32_e32 v0, 10, v0
	v_mul_i32_i24_e32 v1, 0x400, v0
	v_sub_u32_e32 v1, v144, v1
	v_lshrrev_b32_e32 v2, 4, v1
	v_readlane_b32 s2, v255, 0
	v_bitop3_b32 v1, v2, v1, 32 bitop3:0x6c
	v_readlane_b32 s3, v255, 1
	v_ashrrev_i32_e32 v4, 31, v1
	s_load_dwordx2 s[2:3], s[2:3], 0x98
	v_lshrrev_b32_e32 v4, 26, v4
	v_add_u32_e32 v4, v1, v4
	v_lshrrev_b32_e32 v5, 6, v4
	v_and_b32_e32 v4, 0xc0, v4
	v_lshlrev_b32_e32 v2, 3, v0
	v_lshlrev_b32_e32 v0, 5, v0
	v_sub_u32_e32 v1, v1, v4
	s_and_b32 s9, s19, 0xffff
	s_and_b32 s13, s21, 0xffff
	v_and_b32_e32 v2, 0x1ffff0, v2
	v_and_b32_e32 v0, 32, v0
	v_ashrrev_i16_sdwa v1, v3, sext(v1) dst_sel:DWORD dst_unused:UNUSED_PAD src0_sel:DWORD src1_sel:BYTE_0
	s_lshl_b64 s[0:1], s[0:1], 2
	v_add_u32_sdwa v0, v0, sext(v1) dst_sel:DWORD dst_unused:UNUSED_PAD src0_sel:DWORD src1_sel:WORD_0
	v_add_lshl_u32 v1, v5, v2, 11
	s_waitcnt lgkmcnt(0)
	s_add_u32 s2, s2, s0
	v_lshl_add_u32 v145, v0, 1, v1
	s_addc_u32 s3, s3, s1
	s_and_b32 s4, s38, 3
	s_ashr_i32 s5, s38, 2
	v_lshlrev_b32_e32 v0, 6, v140
	v_lshlrev_b32_e32 v2, 2, v156
	s_cmp_eq_u32 s5, 1
	v_or_b32_e32 v1, v128, v0
	v_and_b32_e32 v2, 32, v2
	s_mov_b32 s7, 0x10000
	s_cselect_b64 s[0:1], -1, 0
	s_lshl_b32 s6, s4, 12
	v_bitop3_b32 v3, v1, s7, v2 bitop3:0xde
	s_lshl_b32 s40, s5, 6
	s_mov_b32 s7, 0x14000
	v_bitop3_b32 v4, v1, s7, v2 bitop3:0xde
	s_mov_b32 s7, 0x18000
	s_cmp_lt_u32 s38, 4
	v_bitop3_b32 v5, v1, s7, v2 bitop3:0xde
	s_mov_b32 s7, 0x1c000
	s_cselect_b64 s[22:23], -1, 0
	s_lshl_b32 s5, s5, 13
	v_bitop3_b32 v1, v1, s7, v2 bitop3:0xde
	s_or_b32 s7, s5, 0x800
	s_or_b32 s30, s5, 0x1000
	s_or_b32 s31, s5, 0x1800
	s_add_u32 s24, s16, 0x4442000
	s_addc_u32 s25, s17, 0
	v_lshlrev_b32_e32 v6, 6, v156
	s_add_u32 s26, s2, 0x1dc60000
	v_and_b32_e32 v6, 0x3c0, v6
	s_addc_u32 s27, s3, 0
	s_mov_b32 s11, 0x20000
	v_bitop3_b32 v0, v128, v2, v0 bitop3:0x36
	v_bitop3_b32 v2, v6, v2, v128 bitop3:0x36
	s_add_u32 s28, s2, 0x1dc00000
	v_cndmask_b32_e64 v6, 0, 1, s[0:1]
	s_mov_b32 s10, 0x2200000
	s_mov_b32 s8, s18
	s_mov_b32 s14, 0xc00000
	s_mov_b32 s15, s11
	s_mov_b32 s12, s20
	v_lshlrev_b32_e32 v146, 2, v129
	v_add_u32_e32 v147, 0x10000, v142
	v_add_u32_e32 v148, 0x12000, v142
	v_add_u32_e32 v149, 0x14000, v142
	v_add_u32_e32 v150, 0x16000, v142
	s_movk_i32 s41, 0x4000
	v_add_u32_e32 v151, 0x4000, v142
	v_add_u32_e32 v152, 0x6000, v142
	v_add_u32_e32 v153, 0x18000, v142
	v_add_u32_e32 v154, 0x1a000, v142
	v_add_u32_e32 v155, 0x8000, v142
	v_add_u32_e32 v157, 0xa000, v142
	v_add_u32_e32 v158, 0x1c000, v142
	v_add_u32_e32 v159, 0x1e000, v142
	v_add_u32_e32 v160, 0xc000, v142
	v_add_u32_e32 v161, 0xe000, v142
	s_addc_u32 s29, s3, 0
	v_lshl_or_b32 v162, s4, 5, v140
	s_movk_i32 s42, 0xcd
	v_add_u32_e32 v163, s6, v3
	v_add_u32_e32 v164, s5, v0
	v_add_u32_e32 v165, s7, v2
	v_add_u32_e32 v166, s30, v2
	v_add_u32_e32 v167, s31, v2
	v_add_u32_e32 v168, s6, v4
	v_add_u32_e32 v169, s6, v5
	v_add_u32_e32 v170, s6, v1
	v_mov_b32_e32 v131, 0
	s_movk_i32 s43, 0x3080
	s_movk_i32 s44, 0x3fff
	s_movk_i32 s45, 0x7fd
	s_movk_i32 s46, 0x7fc
	v_cmp_ne_u32_e64 s[2:3], 1, v6
	s_mov_b32 s47, s78
	s_waitcnt vmcnt(0)
	s_branch .LBB0_1058
.LBB0_1058:
	s_mul_hi_i32 s0, s47, 0xa0a0a0a1
	s_add_i32 s0, s0, s47
	s_lshr_b32 s1, s0, 31
	s_lshr_b32 s0, s0, 10
	s_add_i32 s0, s0, s1
	s_mulk_i32 s0, 0x660
	s_sub_i32 s0, s47, s0
	s_sext_i32_i16 s1, s0
	s_bfe_u32 s1, s1, 0x3001c
	s_add_i32 s1, s0, s1
	s_sext_i32_i16 s4, s1
	s_and_b32 s1, s1, 0xfff8
	s_sub_i32 s0, s0, s1
	s_ashr_i32 s4, s4, 3
	s_sext_i32_i16 s1, s0
	s_cmp_lt_i32 s1, 0
	s_cselect_b32 s1, s42, 0xcc
	s_mul_i32 s0, s1, s0
	s_add_i32 s0, s0, s4
	s_sext_i32_i16 s1, s0
	s_mulk_i32 s1, 0x2aab
	s_lshr_b32 s4, s1, 31
	s_ashr_i32 s7, s1, 20
	s_add_i32 s7, s7, s4
	s_mul_i32 s1, s7, 0x60
	s_sub_i32 s0, s0, s1
	s_bfe_i32 s1, s0, 0x80000
	s_bfe_u32 s1, s1, 0x2000d
	s_add_i32 s1, s0, s1
	s_bfe_i32 s5, s1, 0x80000
	s_and_b32 s1, s1, 0xfc
	s_sext_i32_i16 s5, s5
	s_sub_i32 s1, s0, s1
	s_sext_i32_i8 s30, s1
	s_ashr_i32 s1, s5, 2
	v_readfirstlane_b32 s5, v147
	s_lshl_b32 s4, s7, 2
	s_lshl_b32 s6, s1, 19
	s_mov_b32 m0, s5
	v_readfirstlane_b32 s5, v148
	s_add_i32 s4, s4, s30
	buffer_load_dwordx4 v143, s[12:15], s6 offen lds
	s_mov_b32 m0, s5
	v_readfirstlane_b32 s31, v142
	buffer_load_dwordx4 v145, s[12:15], s6 offen lds
	s_lshl_b32 s5, s4, 19
	s_mov_b32 m0, s31
	v_readfirstlane_b32 s31, v144
	buffer_load_dwordx4 v143, s[8:11], s5 offen lds
	s_mov_b32 m0, s31
	v_readfirstlane_b32 s33, v149
	buffer_load_dwordx4 v145, s[8:11], s5 offen lds
	s_or_b32 s31, s6, 0x40000
	s_mov_b32 m0, s33
	v_readfirstlane_b32 s33, v150
	buffer_load_dwordx4 v143, s[12:15], s31 offen lds
	s_mov_b32 m0, s33
	v_readfirstlane_b32 s33, v151
	buffer_load_dwordx4 v145, s[12:15], s31 offen lds
	s_or_b32 s31, s5, 0x40000
	s_mov_b32 m0, s33
	v_readfirstlane_b32 s33, v152
	buffer_load_dwordx4 v143, s[8:11], s31 offen lds
	s_mov_b32 m0, s33
	s_and_b64 vcc, exec, s[2:3]
	buffer_load_dwordx4 v145, s[8:11], s31 offen lds
	s_cbranch_vccnz .LBB0_1060
	s_barrier

; #define WAIT_V(n) asm volatile("s_waitcnt vmcnt(" #n ")" ::: "memory")
; #define WAIT_L(n) asm volatile("s_waitcnt lgkmcnt(" #n ")" ::: "memory")
; #define BAR __builtin_amdgcn_s_barrier()
; #define SCHED __builtin_amdgcn_sched_barrier(0)
; template <int EPI>
; __device__ void gemm8_phase(const Params& p, const u16* __restrict__ A, const u16* __restrict__ Bt, const int K, const int nN,
;                             unsigned char* smem, const int rep) {
;     ...
;     for (int t = 0; t < nt - 2; t += 2) {
;       LDB(B0, 0, 0); SCHED; LDA(At, 0, 0); STAGE(SA(1, 1), A, brow + HALF, t + 1);
;       WAIT_L(8); BAR; WAIT_L(0); MMA(0, 0, At, B0); BAR; SCHED;
;       LDB(B1, 0, 1); STAGE(SB(0, 0), Bt, bcol, t + 2);
;       BAR; WAIT_L(0); MMA(0, 1, At, B1); BAR;
;       LDA(At, 0, 1); STAGE(SA(0, 0), A, brow, t + 2);
;       BAR; WAIT_L(0); MMA(1, 0, At, B0); BAR; SCHED;
;       STAGE(SB(0, 1), Bt, bcol + HALF, t + 2);
;       WAIT_V(6); BAR; MMA(1, 1, At, B1); BAR;
.LBB0_1061:
	ds_read_b128 v[132:135], v163
	ds_read_b128 v[136:139], v163 offset:1024
	ds_read_b128 v[172:175], v163 offset:2048
	ds_read_b128 v[176:179], v163 offset:3072
	s_add_i32 s33, s7, s31
	v_readfirstlane_b32 s35, v160
	s_or_b32 s34, s33, 0x40080
	s_mov_b32 m0, s35
	v_readfirstlane_b32 s35, v161
	ds_read_b128 v[180:183], v164
	ds_read_b128 v[184:187], v164 offset:1024
	ds_read_b128 v[188:191], v165
	ds_read_b128 v[196:199], v165 offset:1024
	ds_read_b128 v[200:203], v166
	ds_read_b128 v[204:207], v166 offset:1024
	ds_read_b128 v[208:211], v167
	ds_read_b128 v[212:215], v167 offset:1024
	buffer_load_dwordx4 v143, s[8:11], s34 offen lds
	s_mov_b32 m0, s35
	s_nop 0
	buffer_load_dwordx4 v145, s[8:11], s34 offen lds
	s_waitcnt lgkmcnt(8)
	s_barrier
	s_waitcnt lgkmcnt(0)
	s_setprio 1
	s_waitcnt lgkmcnt(7)
	v_mfma_f32_16x16x32_bf16 v[124:127], v[132:135], v[180:183], v[124:127]
	v_mfma_f32_16x16x32_bf16 v[120:123], v[172:175], v[180:183], v[120:123]
	s_waitcnt lgkmcnt(5)
	v_mfma_f32_16x16x32_bf16 v[116:119], v[132:135], v[188:191], v[116:119]
	v_mfma_f32_16x16x32_bf16 v[112:115], v[172:175], v[188:191], v[112:115]
	s_waitcnt lgkmcnt(3)
	v_mfma_f32_16x16x32_bf16 v[108:111], v[132:135], v[200:203], v[108:111]
	v_mfma_f32_16x16x32_bf16 v[104:107], v[172:175], v[200:203], v[104:107]
	s_waitcnt lgkmcnt(1)
	v_mfma_f32_16x16x32_bf16 v[100:103], v[132:135], v[208:211], v[100:103]
	v_mfma_f32_16x16x32_bf16 v[96:99], v[172:175], v[208:211], v[96:99]
	v_mfma_f32_16x16x32_bf16 v[124:127], v[136:139], v[184:187], v[124:127]
	v_mfma_f32_16x16x32_bf16 v[120:123], v[176:179], v[184:187], v[120:123]
	v_mfma_f32_16x16x32_bf16 v[116:119], v[136:139], v[196:199], v[116:119]
	v_mfma_f32_16x16x32_bf16 v[112:115], v[176:179], v[196:199], v[112:115]
	v_mfma_f32_16x16x32_bf16 v[108:111], v[136:139], v[204:207], v[108:111]
	v_mfma_f32_16x16x32_bf16 v[104:107], v[176:179], v[204:207], v[104:107]
	s_waitcnt lgkmcnt(0)
	v_mfma_f32_16x16x32_bf16 v[100:103], v[136:139], v[212:215], v[100:103]
	v_mfma_f32_16x16x32_bf16 v[96:99], v[176:179], v[212:215], v[96:99]
	s_setprio 0
	s_barrier
	s_add_i32 s34, s6, s31
	v_readfirstlane_b32 s36, v147
	s_add_i32 s35, s34, 0x100
	s_mov_b32 m0, s36
	v_readfirstlane_b32 s36, v148
	ds_read_b128 v[216:219], v168
	ds_read_b128 v[220:223], v168 offset:1024
	ds_read_b128 v[224:227], v168 offset:2048
	ds_read_b128 v[228:231], v168 offset:3072
	buffer_load_dwordx4 v143, s[12:15], s35 offen lds
	s_mov_b32 m0, s36
	s_nop 0
	buffer_load_dwordx4 v145, s[12:15], s35 offen lds
	s_barrier
	s_waitcnt lgkmcnt(0)
	s_setprio 1
	s_waitcnt lgkmcnt(3)
	v_mfma_f32_16x16x32_bf16 v[92:95], v[216:219], v[180:183], v[92:95]
	s_waitcnt lgkmcnt(1)
	v_mfma_f32_16x16x32_bf16 v[88:91], v[224:227], v[180:183], v[88:91]
	v_mfma_f32_16x16x32_bf16 v[84:87], v[216:219], v[188:191], v[84:87]
	v_mfma_f32_16x16x32_bf16 v[80:83], v[224:227], v[188:191], v[80:83]
	v_mfma_f32_16x16x32_bf16 v[76:79], v[216:219], v[200:203], v[76:79]
	v_mfma_f32_16x16x32_bf16 v[72:75], v[224:227], v[200:203], v[72:75]
	v_mfma_f32_16x16x32_bf16 v[68:71], v[216:219], v[208:211], v[68:71]
	v_mfma_f32_16x16x32_bf16 v[64:67], v[224:227], v[208:211], v[64:67]
	v_mfma_f32_16x16x32_bf16 v[92:95], v[220:223], v[184:187], v[92:95]
	s_waitcnt lgkmcnt(0)
	v_mfma_f32_16x16x32_bf16 v[88:91], v[228:231], v[184:187], v[88:91]
	v_mfma_f32_16x16x32_bf16 v[84:87], v[220:223], v[196:199], v[84:87]
	v_mfma_f32_16x16x32_bf16 v[80:83], v[228:231], v[196:199], v[80:83]
	v_mfma_f32_16x16x32_bf16 v[76:79], v[220:223], v[204:207], v[76:79]
	v_mfma_f32_16x16x32_bf16 v[72:75], v[228:231], v[204:207], v[72:75]
	v_mfma_f32_16x16x32_bf16 v[68:71], v[220:223], v[212:215], v[68:71]
	v_mfma_f32_16x16x32_bf16 v[64:67], v[228:231], v[212:215], v[64:67]
	s_setprio 0
	v_readfirstlane_b32 s36, v142
	s_add_i32 s35, s33, 0x100
	s_mov_b32 m0, s36
	v_readfirstlane_b32 s36, v144
	s_barrier
	ds_read_b128 v[180:183], v164 offset:16384
	ds_read_b128 v[184:187], v164 offset:17408
	ds_read_b128 v[188:191], v165 offset:16384
	ds_read_b128 v[196:199], v165 offset:17408
	ds_read_b128 v[200:203], v166 offset:16384
	ds_read_b128 v[204:207], v166 offset:17408
	ds_read_b128 v[208:211], v167 offset:16384
	ds_read_b128 v[212:215], v167 offset:17408
	buffer_load_dwordx4 v143, s[8:11], s35 offen lds
	s_mov_b32 m0, s36
	s_nop 0
	buffer_load_dwordx4 v145, s[8:11], s35 offen lds
	s_barrier
	s_waitcnt lgkmcnt(0)
	s_setprio 1
	s_waitcnt lgkmcnt(7)
	v_mfma_f32_16x16x32_bf16 v[60:63], v[132:135], v[180:183], v[60:63]
	v_mfma_f32_16x16x32_bf16 v[56:59], v[172:175], v[180:183], v[56:59]
	s_waitcnt lgkmcnt(5)
	v_mfma_f32_16x16x32_bf16 v[52:55], v[132:135], v[188:191], v[52:55]
	v_mfma_f32_16x16x32_bf16 v[48:51], v[172:175], v[188:191], v[48:51]
	s_waitcnt lgkmcnt(3)
	v_mfma_f32_16x16x32_bf16 v[44:47], v[132:135], v[200:203], v[44:47]
	v_mfma_f32_16x16x32_bf16 v[40:43], v[172:175], v[200:203], v[40:43]
	s_waitcnt lgkmcnt(1)
	v_mfma_f32_16x16x32_bf16 v[36:39], v[132:135], v[208:211], v[36:39]
	v_mfma_f32_16x16x32_bf16 v[32:35], v[172:175], v[208:211], v[32:35]
	v_mfma_f32_16x16x32_bf16 v[60:63], v[136:139], v[184:187], v[60:63]
	v_mfma_f32_16x16x32_bf16 v[56:59], v[176:179], v[184:187], v[56:59]
	v_mfma_f32_16x16x32_bf16 v[52:55], v[136:139], v[196:199], v[52:55]
	v_mfma_f32_16x16x32_bf16 v[48:51], v[176:179], v[196:199], v[48:51]
	v_mfma_f32_16x16x32_bf16 v[44:47], v[136:139], v[204:207], v[44:47]
	v_mfma_f32_16x16x32_bf16 v[40:43], v[176:179], v[204:207], v[40:43]
	s_waitcnt lgkmcnt(0)
	v_mfma_f32_16x16x32_bf16 v[36:39], v[136:139], v[212:215], v[36:39]
	v_mfma_f32_16x16x32_bf16 v[32:35], v[176:179], v[212:215], v[32:35]
	s_setprio 0
	s_barrier
; #define WAIT_V(n) asm volatile("s_waitcnt vmcnt(" #n ")" ::: "memory")
; #define WAIT_L(n) asm volatile("s_waitcnt lgkmcnt(" #n ")" ::: "memory")
; #define BAR __builtin_amdgcn_s_barrier()
; #define SCHED __builtin_amdgcn_sched_barrier(0)
; template <int EPI>
; __device__ void gemm8_phase(const Params& p, const u16* __restrict__ A, const u16* __restrict__ Bt, const int K, const int nN,
;                             unsigned char* smem, const int rep) {
;     ...
;       WAIT_V(6); BAR; MMA(1, 1, At, B1); BAR;
;       LDB(B0, 1, 0); SCHED; LDA(At, 1, 0); STAGE(SA(0, 1), A, brow + HALF, t + 2);
;       WAIT_L(8); BAR; WAIT_L(0); MMA(0, 0, At, B0); BAR; SCHED;
;       LDB(B1, 1, 1); STAGE(SB(1, 0), Bt, bcol, t + 3);
;       BAR; WAIT_L(0); MMA(0, 1, At, B1); BAR;
;       LDA(At, 1, 1); STAGE(SA(1, 0), A, brow, t + 3);
;       BAR; WAIT_L(0); MMA(1, 0, At, B0); BAR; SCHED;
	v_readfirstlane_b32 s36, v149
	s_add_i32 s35, s34, 0x40100
	s_mov_b32 m0, s36
	v_readfirstlane_b32 s36, v150
	buffer_load_dwordx4 v143, s[12:15], s35 offen lds
	s_mov_b32 m0, s36
	s_nop 0
	buffer_load_dwordx4 v145, s[12:15], s35 offen lds
	s_waitcnt vmcnt(6)
	s_barrier
	s_setprio 1
	v_mfma_f32_16x16x32_bf16 v[28:31], v[216:219], v[180:183], v[28:31]
	v_mfma_f32_16x16x32_bf16 v[24:27], v[224:227], v[180:183], v[24:27]
	v_mfma_f32_16x16x32_bf16 v[20:23], v[216:219], v[188:191], v[20:23]
	v_mfma_f32_16x16x32_bf16 v[16:19], v[224:227], v[188:191], v[16:19]
	v_mfma_f32_16x16x32_bf16 v[12:15], v[216:219], v[200:203], v[12:15]
	v_mfma_f32_16x16x32_bf16 v[8:11], v[224:227], v[200:203], v[8:11]
	v_mfma_f32_16x16x32_bf16 v[4:7], v[216:219], v[208:211], v[4:7]
	v_mfma_f32_16x16x32_bf16 v[0:3], v[224:227], v[208:211], v[0:3]
	v_mfma_f32_16x16x32_bf16 v[28:31], v[220:223], v[184:187], v[28:31]
	v_mfma_f32_16x16x32_bf16 v[24:27], v[228:231], v[184:187], v[24:27]
	v_mfma_f32_16x16x32_bf16 v[20:23], v[220:223], v[196:199], v[20:23]
	v_mfma_f32_16x16x32_bf16 v[16:19], v[228:231], v[196:199], v[16:19]
	v_mfma_f32_16x16x32_bf16 v[12:15], v[220:223], v[204:207], v[12:15]
	v_mfma_f32_16x16x32_bf16 v[8:11], v[228:231], v[204:207], v[8:11]
	v_mfma_f32_16x16x32_bf16 v[4:7], v[220:223], v[212:215], v[4:7]
	v_mfma_f32_16x16x32_bf16 v[0:3], v[228:231], v[212:215], v[0:3]
	s_setprio 0
	s_barrier
	ds_read_b128 v[132:135], v169
	ds_read_b128 v[136:139], v169 offset:1024
	ds_read_b128 v[172:175], v169 offset:2048
	ds_read_b128 v[176:179], v169 offset:3072
	v_readfirstlane_b32 s36, v151
	s_add_i32 s35, s33, 0x40100
	s_mov_b32 m0, s36
	v_readfirstlane_b32 s36, v152
	ds_read_b128 v[180:183], v164 offset:32768
	ds_read_b128 v[184:187], v164 offset:33792
	ds_read_b128 v[188:191], v165 offset:32768
	ds_read_b128 v[196:199], v165 offset:33792
	ds_read_b128 v[200:203], v166 offset:32768
	ds_read_b128 v[204:207], v166 offset:33792
	ds_read_b128 v[208:211], v167 offset:32768
	ds_read_b128 v[212:215], v167 offset:33792
	buffer_load_dwordx4 v143, s[8:11], s35 offen lds
	s_mov_b32 m0, s36
	s_nop 0
	buffer_load_dwordx4 v145, s[8:11], s35 offen lds
	s_waitcnt lgkmcnt(8)
	s_barrier
	s_waitcnt lgkmcnt(0)
	s_setprio 1
	s_waitcnt lgkmcnt(7)
	v_mfma_f32_16x16x32_bf16 v[124:127], v[132:135], v[180:183], v[124:127]
	v_mfma_f32_16x16x32_bf16 v[120:123], v[172:175], v[180:183], v[120:123]
	s_waitcnt lgkmcnt(5)
	v_mfma_f32_16x16x32_bf16 v[116:119], v[132:135], v[188:191], v[116:119]
	v_mfma_f32_16x16x32_bf16 v[112:115], v[172:175], v[188:191], v[112:115]
	s_waitcnt lgkmcnt(3)
	v_mfma_f32_16x16x32_bf16 v[108:111], v[132:135], v[200:203], v[108:111]
	v_mfma_f32_16x16x32_bf16 v[104:107], v[172:175], v[200:203], v[104:107]
	s_waitcnt lgkmcnt(1)
	v_mfma_f32_16x16x32_bf16 v[100:103], v[132:135], v[208:211], v[100:103]
	v_mfma_f32_16x16x32_bf16 v[96:99], v[172:175], v[208:211], v[96:99]
	v_mfma_f32_16x16x32_bf16 v[124:127], v[136:139], v[184:187], v[124:127]
	v_mfma_f32_16x16x32_bf16 v[120:123], v[176:179], v[184:187], v[120:123]
	v_mfma_f32_16x16x32_bf16 v[116:119], v[136:139], v[196:199], v[116:119]
	v_mfma_f32_16x16x32_bf16 v[112:115], v[176:179], v[196:199], v[112:115]
	v_mfma_f32_16x16x32_bf16 v[108:111], v[136:139], v[204:207], v[108:111]
	v_mfma_f32_16x16x32_bf16 v[104:107], v[176:179], v[204:207], v[104:107]
	s_waitcnt lgkmcnt(0)
	v_mfma_f32_16x16x32_bf16 v[100:103], v[136:139], v[212:215], v[100:103]
	v_mfma_f32_16x16x32_bf16 v[96:99], v[176:179], v[212:215], v[96:99]
	s_setprio 0
	s_barrier
	v_readfirstlane_b32 s36, v153
	s_add_i32 s35, s34, 0x180
	s_mov_b32 m0, s36
	v_readfirstlane_b32 s36, v154
	ds_read_b128 v[216:219], v170
	ds_read_b128 v[220:223], v170 offset:1024
	ds_read_b128 v[224:227], v170 offset:2048
	ds_read_b128 v[228:231], v170 offset:3072
	buffer_load_dwordx4 v143, s[12:15], s35 offen lds
	s_mov_b32 m0, s36
	s_nop 0
	buffer_load_dwordx4 v145, s[12:15], s35 offen lds
	s_barrier
	s_waitcnt lgkmcnt(0)
	s_setprio 1
	s_waitcnt lgkmcnt(3)
	v_mfma_f32_16x16x32_bf16 v[92:95], v[216:219], v[180:183], v[92:95]
	s_waitcnt lgkmcnt(1)
	v_mfma_f32_16x16x32_bf16 v[88:91], v[224:227], v[180:183], v[88:91]
	v_mfma_f32_16x16x32_bf16 v[84:87], v[216:219], v[188:191], v[84:87]
	v_mfma_f32_16x16x32_bf16 v[80:83], v[224:227], v[188:191], v[80:83]
	v_mfma_f32_16x16x32_bf16 v[76:79], v[216:219], v[200:203], v[76:79]
	v_mfma_f32_16x16x32_bf16 v[72:75], v[224:227], v[200:203], v[72:75]
	v_mfma_f32_16x16x32_bf16 v[68:71], v[216:219], v[208:211], v[68:71]
	v_mfma_f32_16x16x32_bf16 v[64:67], v[224:227], v[208:211], v[64:67]
	v_mfma_f32_16x16x32_bf16 v[92:95], v[220:223], v[184:187], v[92:95]
	s_waitcnt lgkmcnt(0)
	v_mfma_f32_16x16x32_bf16 v[88:91], v[228:231], v[184:187], v[88:91]
	v_mfma_f32_16x16x32_bf16 v[84:87], v[220:223], v[196:199], v[84:87]
	v_mfma_f32_16x16x32_bf16 v[80:83], v[228:231], v[196:199], v[80:83]
	v_mfma_f32_16x16x32_bf16 v[76:79], v[220:223], v[204:207], v[76:79]
	v_mfma_f32_16x16x32_bf16 v[72:75], v[228:231], v[204:207], v[72:75]
	v_mfma_f32_16x16x32_bf16 v[68:71], v[220:223], v[212:215], v[68:71]
	v_mfma_f32_16x16x32_bf16 v[64:67], v[228:231], v[212:215], v[64:67]
	s_setprio 0
	v_readfirstlane_b32 s35, v155
	s_addk_i32 s33, 0x180
	s_mov_b32 m0, s35
	v_readfirstlane_b32 s35, v157
	s_barrier
	ds_read_b128 v[180:183], v164 offset:49152
	ds_read_b128 v[184:187], v164 offset:50176
	ds_read_b128 v[188:191], v165 offset:49152
	ds_read_b128 v[196:199], v165 offset:50176
	ds_read_b128 v[200:203], v166 offset:49152
	ds_read_b128 v[204:207], v166 offset:50176
	ds_read_b128 v[208:211], v167 offset:49152
	ds_read_b128 v[212:215], v167 offset:50176
	buffer_load_dwordx4 v143, s[8:11], s33 offen lds
	s_mov_b32 m0, s35
	s_nop 0
	buffer_load_dwordx4 v145, s[8:11], s33 offen lds
	s_barrier
; #define WAIT_V(n) asm volatile("s_waitcnt vmcnt(" #n ")" ::: "memory")
; #define WAIT_L(n) asm volatile("s_waitcnt lgkmcnt(" #n ")" ::: "memory")
; #define BAR __builtin_amdgcn_s_barrier()
; #define SCHED __builtin_amdgcn_sched_barrier(0)
; template <int EPI>
; __device__ void gemm8_phase(const Params& p, const u16* __restrict__ A, const u16* __restrict__ Bt, const int K, const int nN,
;                             unsigned char* smem, const int rep) {
;     ...
;       STAGE(SB(1, 1), Bt, bcol + HALF, t + 3);
;       WAIT_V(6); BAR; MMA(1, 1, At, B1); BAR;
;     }
;     {
;       LDB(B0, 0, 0); LDA(At, 0, 0); STAGE(SA(1, 1), A, brow + HALF, nt - 1);
;       BAR; WAIT_L(0); MMA(0, 0, At, B0); BAR; SCHED;
;       LDB(B1, 0, 1); BAR; WAIT_L(0); MMA(0, 1, At, B1); BAR; SCHED;
;       LDA(At, 0, 1); WAIT_V(4); BAR; WAIT_L(0); MMA(1, 0, At, B0); MMA(1, 1, At, B1); BAR; SCHED;
	s_waitcnt lgkmcnt(0)
	s_setprio 1
	s_waitcnt lgkmcnt(7)
	v_mfma_f32_16x16x32_bf16 v[60:63], v[132:135], v[180:183], v[60:63]
	v_mfma_f32_16x16x32_bf16 v[56:59], v[172:175], v[180:183], v[56:59]
	s_waitcnt lgkmcnt(5)
	v_mfma_f32_16x16x32_bf16 v[52:55], v[132:135], v[188:191], v[52:55]
	v_mfma_f32_16x16x32_bf16 v[48:51], v[172:175], v[188:191], v[48:51]
	s_waitcnt lgkmcnt(3)
	v_mfma_f32_16x16x32_bf16 v[44:47], v[132:135], v[200:203], v[44:47]
	v_mfma_f32_16x16x32_bf16 v[40:43], v[172:175], v[200:203], v[40:43]
	s_waitcnt lgkmcnt(1)
	v_mfma_f32_16x16x32_bf16 v[36:39], v[132:135], v[208:211], v[36:39]
	v_mfma_f32_16x16x32_bf16 v[32:35], v[172:175], v[208:211], v[32:35]
	v_mfma_f32_16x16x32_bf16 v[60:63], v[136:139], v[184:187], v[60:63]
	v_mfma_f32_16x16x32_bf16 v[56:59], v[176:179], v[184:187], v[56:59]
	v_mfma_f32_16x16x32_bf16 v[52:55], v[136:139], v[196:199], v[52:55]
	v_mfma_f32_16x16x32_bf16 v[48:51], v[176:179], v[196:199], v[48:51]
	v_mfma_f32_16x16x32_bf16 v[44:47], v[136:139], v[204:207], v[44:47]
	v_mfma_f32_16x16x32_bf16 v[40:43], v[176:179], v[204:207], v[40:43]
	s_waitcnt lgkmcnt(0)
	v_mfma_f32_16x16x32_bf16 v[36:39], v[136:139], v[212:215], v[36:39]
	v_mfma_f32_16x16x32_bf16 v[32:35], v[176:179], v[212:215], v[32:35]
	s_setprio 0
	s_barrier
	v_readfirstlane_b32 s33, v158
	s_add_i32 s34, s34, 0x40180
	s_mov_b32 m0, s33
	v_readfirstlane_b32 s33, v159
	buffer_load_dwordx4 v143, s[12:15], s34 offen lds
	s_mov_b32 m0, s33
	s_nop 0
	buffer_load_dwordx4 v145, s[12:15], s34 offen lds
	s_waitcnt vmcnt(6)
	s_barrier
	s_setprio 1
	v_mfma_f32_16x16x32_bf16 v[28:31], v[216:219], v[180:183], v[28:31]
	v_mfma_f32_16x16x32_bf16 v[24:27], v[224:227], v[180:183], v[24:27]
	v_mfma_f32_16x16x32_bf16 v[20:23], v[216:219], v[188:191], v[20:23]
	v_mfma_f32_16x16x32_bf16 v[16:19], v[224:227], v[188:191], v[16:19]
	v_mfma_f32_16x16x32_bf16 v[12:15], v[216:219], v[200:203], v[12:15]
	v_mfma_f32_16x16x32_bf16 v[8:11], v[224:227], v[200:203], v[8:11]
	v_mfma_f32_16x16x32_bf16 v[4:7], v[216:219], v[208:211], v[4:7]
	v_mfma_f32_16x16x32_bf16 v[0:3], v[224:227], v[208:211], v[0:3]
	v_mfma_f32_16x16x32_bf16 v[28:31], v[220:223], v[184:187], v[28:31]
	v_mfma_f32_16x16x32_bf16 v[24:27], v[228:231], v[184:187], v[24:27]
	v_mfma_f32_16x16x32_bf16 v[20:23], v[220:223], v[196:199], v[20:23]
	v_mfma_f32_16x16x32_bf16 v[16:19], v[228:231], v[196:199], v[16:19]
	v_mfma_f32_16x16x32_bf16 v[12:15], v[220:223], v[204:207], v[12:15]
	v_mfma_f32_16x16x32_bf16 v[8:11], v[228:231], v[204:207], v[8:11]
	v_mfma_f32_16x16x32_bf16 v[4:7], v[220:223], v[212:215], v[4:7]
	v_mfma_f32_16x16x32_bf16 v[0:3], v[228:231], v[212:215], v[0:3]
	s_setprio 0
	s_add_i32 s30, s30, 2
	s_addk_i32 s31, 0x100
	s_cmp_lt_u32 s30, 12
	s_barrier
	s_cbranch_scc1 .LBB0_1061
	v_readfirstlane_b32 s6, v160
	s_or_b32 s5, s5, 0x40780
	s_mov_b32 m0, s6
	v_readfirstlane_b32 s6, v161
	ds_read_b128 v[132:135], v163
	ds_read_b128 v[136:139], v163 offset:1024
	ds_read_b128 v[172:175], v163 offset:2048
	ds_read_b128 v[176:179], v163 offset:3072
	ds_read_b128 v[180:183], v164
	ds_read_b128 v[184:187], v164 offset:1024
	ds_read_b128 v[188:191], v165
	ds_read_b128 v[196:199], v165 offset:1024
	ds_read_b128 v[200:203], v166
	ds_read_b128 v[204:207], v166 offset:1024
	ds_read_b128 v[208:211], v167
	ds_read_b128 v[212:215], v167 offset:1024
	buffer_load_dwordx4 v143, s[8:11], s5 offen lds
	s_mov_b32 m0, s6
	s_nop 0
	buffer_load_dwordx4 v145, s[8:11], s5 offen lds
	s_barrier
	s_waitcnt lgkmcnt(0)
	s_setprio 1
	s_waitcnt lgkmcnt(7)
	v_mfma_f32_16x16x32_bf16 v[124:127], v[132:135], v[180:183], v[124:127]
	v_mfma_f32_16x16x32_bf16 v[120:123], v[172:175], v[180:183], v[120:123]
	s_waitcnt lgkmcnt(5)
	v_mfma_f32_16x16x32_bf16 v[112:115], v[172:175], v[188:191], v[112:115]
	s_waitcnt lgkmcnt(3)
	v_mfma_f32_16x16x32_bf16 v[104:107], v[172:175], v[200:203], v[104:107]
	s_waitcnt lgkmcnt(1)
	v_mfma_f32_16x16x32_bf16 v[96:99], v[172:175], v[208:211], v[96:99]
	v_mfma_f32_16x16x32_bf16 v[124:127], v[136:139], v[184:187], v[124:127]
	v_mfma_f32_16x16x32_bf16 v[120:123], v[176:179], v[184:187], v[120:123]
	v_mfma_f32_16x16x32_bf16 v[116:119], v[132:135], v[188:191], v[116:119]
	v_mfma_f32_16x16x32_bf16 v[112:115], v[176:179], v[196:199], v[112:115]
	v_mfma_f32_16x16x32_bf16 v[108:111], v[132:135], v[200:203], v[108:111]
	v_mfma_f32_16x16x32_bf16 v[104:107], v[176:179], v[204:207], v[104:107]
	v_mfma_f32_16x16x32_bf16 v[100:103], v[132:135], v[208:211], v[100:103]
	s_waitcnt lgkmcnt(0)
	v_mfma_f32_16x16x32_bf16 v[96:99], v[176:179], v[212:215], v[96:99]
	v_mfma_f32_16x16x32_bf16 v[216:219], v[136:139], v[196:199], v[116:119]
	v_mfma_f32_16x16x32_bf16 v[220:223], v[136:139], v[204:207], v[108:111]
	v_mfma_f32_16x16x32_bf16 v[224:227], v[136:139], v[212:215], v[100:103]
	s_setprio 0
	s_barrier
	s_nop 0
	ds_read_b128 v[100:103], v168
	ds_read_b128 v[108:111], v168 offset:1024
	ds_read_b128 v[116:119], v168 offset:2048
	ds_read_b128 v[228:231], v168 offset:3072
	s_barrier
	s_waitcnt lgkmcnt(0)
	s_setprio 1
	s_waitcnt lgkmcnt(1)
	v_mfma_f32_16x16x32_bf16 v[88:91], v[116:119], v[180:183], v[88:91]
	v_mfma_f32_16x16x32_bf16 v[80:83], v[116:119], v[188:191], v[80:83]
	v_mfma_f32_16x16x32_bf16 v[72:75], v[116:119], v[200:203], v[72:75]
	v_mfma_f32_16x16x32_bf16 v[64:67], v[116:119], v[208:211], v[64:67]
	v_mfma_f32_16x16x32_bf16 v[92:95], v[100:103], v[180:183], v[92:95]
	s_waitcnt lgkmcnt(0)
	v_mfma_f32_16x16x32_bf16 v[88:91], v[228:231], v[184:187], v[88:91]
	v_mfma_f32_16x16x32_bf16 v[84:87], v[100:103], v[188:191], v[84:87]
	v_mfma_f32_16x16x32_bf16 v[80:83], v[228:231], v[196:199], v[80:83]
	v_mfma_f32_16x16x32_bf16 v[76:79], v[100:103], v[200:203], v[76:79]
	v_mfma_f32_16x16x32_bf16 v[72:75], v[228:231], v[204:207], v[72:75]
	v_mfma_f32_16x16x32_bf16 v[68:71], v[100:103], v[208:211], v[68:71]
	v_mfma_f32_16x16x32_bf16 v[64:67], v[228:231], v[212:215], v[64:67]
	v_mfma_f32_16x16x32_bf16 v[232:235], v[108:111], v[184:187], v[92:95]
	v_mfma_f32_16x16x32_bf16 v[180:183], v[108:111], v[196:199], v[84:87]
	v_mfma_f32_16x16x32_bf16 v[184:187], v[108:111], v[204:207], v[76:79]
	v_mfma_f32_16x16x32_bf16 v[188:191], v[108:111], v[212:215], v[68:71]
	s_setprio 0
	s_barrier
; #define WAIT_V(n) asm volatile("s_waitcnt vmcnt(" #n ")" ::: "memory")
; #define WAIT_L(n) asm volatile("s_waitcnt lgkmcnt(" #n ")" ::: "memory")
; #define BAR __builtin_amdgcn_s_barrier()
; #define SCHED __builtin_amdgcn_sched_barrier(0)
; template <int EPI>
; __device__ void gemm8_phase(const Params& p, const u16* __restrict__ A, const u16* __restrict__ Bt, const int K, const int nN,
;                             unsigned char* smem, const int rep) {
;     ...
;       LDB(B0, 0, 0); LDA(At, 0, 0); STAGE(SA(1, 1), A, brow + HALF, nt - 1);
;       BAR; WAIT_L(0); MMA(0, 0, At, B0); BAR; SCHED;
;       LDB(B1, 0, 1); BAR; WAIT_L(0); MMA(0, 1, At, B1); BAR; SCHED;
;       LDA(At, 0, 1); WAIT_V(4); BAR; WAIT_L(0); MMA(1, 0, At, B0); MMA(1, 1, At, B1); BAR; SCHED;
;     }
;     {
;       LDB(B0, 1, 0); LDA(At, 1, 0); WAIT_V(2); BAR; WAIT_L(0); MMA(0, 0, At, B0); BAR; SCHED;
;       LDB(B1, 1, 1); WAIT_V(0); BAR; WAIT_L(0); MMA(0, 1, At, B1); BAR; SCHED;
;       LDA(At, 1, 1); BAR; WAIT_L(0); MMA(1, 0, At, B0); MMA(1, 1, At, B1); BAR; SCHED;
;     }
	s_nop 0
	ds_read_b128 v[68:71], v164 offset:16384
	ds_read_b128 v[76:79], v164 offset:17408
	ds_read_b128 v[84:87], v165 offset:16384
	ds_read_b128 v[92:95], v165 offset:17408
	ds_read_b128 v[196:199], v166 offset:16384
	ds_read_b128 v[200:203], v166 offset:17408
	ds_read_b128 v[204:207], v167 offset:16384
	ds_read_b128 v[208:211], v167 offset:17408
	s_waitcnt vmcnt(4)
	s_barrier
	s_waitcnt lgkmcnt(0)
	s_setprio 1
	s_waitcnt lgkmcnt(7)
	v_mfma_f32_16x16x32_bf16 v[60:63], v[132:135], v[68:71], v[60:63]
	v_mfma_f32_16x16x32_bf16 v[56:59], v[172:175], v[68:71], v[56:59]
	s_waitcnt lgkmcnt(5)
	v_mfma_f32_16x16x32_bf16 v[52:55], v[132:135], v[84:87], v[52:55]
	v_mfma_f32_16x16x32_bf16 v[48:51], v[172:175], v[84:87], v[48:51]
	s_waitcnt lgkmcnt(1)
	v_mfma_f32_16x16x32_bf16 v[36:39], v[132:135], v[204:207], v[36:39]
	v_mfma_f32_16x16x32_bf16 v[32:35], v[172:175], v[204:207], v[32:35]
	v_mfma_f32_16x16x32_bf16 v[60:63], v[136:139], v[76:79], v[60:63]
	v_mfma_f32_16x16x32_bf16 v[56:59], v[176:179], v[76:79], v[56:59]
	v_mfma_f32_16x16x32_bf16 v[52:55], v[136:139], v[92:95], v[52:55]
	v_mfma_f32_16x16x32_bf16 v[48:51], v[176:179], v[92:95], v[48:51]
	v_mfma_f32_16x16x32_bf16 v[44:47], v[132:135], v[196:199], v[44:47]
	v_mfma_f32_16x16x32_bf16 v[40:43], v[172:175], v[196:199], v[40:43]
	s_waitcnt lgkmcnt(0)
	v_mfma_f32_16x16x32_bf16 v[36:39], v[136:139], v[208:211], v[36:39]
	v_mfma_f32_16x16x32_bf16 v[32:35], v[176:179], v[208:211], v[32:35]
	v_mfma_f32_16x16x32_bf16 v[212:215], v[136:139], v[200:203], v[44:47]
	v_mfma_f32_16x16x32_bf16 v[236:239], v[176:179], v[200:203], v[40:43]
	s_setprio 0
	s_setprio 1
	v_mfma_f32_16x16x32_bf16 v[20:23], v[100:103], v[84:87], v[20:23]
	v_mfma_f32_16x16x32_bf16 v[16:19], v[116:119], v[84:87], v[16:19]
	v_mfma_f32_16x16x32_bf16 v[4:7], v[100:103], v[204:207], v[4:7]
	v_mfma_f32_16x16x32_bf16 v[0:3], v[116:119], v[204:207], v[0:3]
	v_mfma_f32_16x16x32_bf16 v[28:31], v[100:103], v[68:71], v[28:31]
	v_mfma_f32_16x16x32_bf16 v[24:27], v[116:119], v[68:71], v[24:27]
	v_mfma_f32_16x16x32_bf16 v[20:23], v[108:111], v[92:95], v[20:23]
	v_mfma_f32_16x16x32_bf16 v[16:19], v[228:231], v[92:95], v[16:19]
	v_mfma_f32_16x16x32_bf16 v[12:15], v[100:103], v[196:199], v[12:15]
	v_mfma_f32_16x16x32_bf16 v[8:11], v[116:119], v[196:199], v[8:11]
	v_mfma_f32_16x16x32_bf16 v[4:7], v[108:111], v[208:211], v[4:7]
	v_mfma_f32_16x16x32_bf16 v[0:3], v[228:231], v[208:211], v[0:3]
	v_mfma_f32_16x16x32_bf16 v[132:135], v[108:111], v[76:79], v[28:31]
	v_mfma_f32_16x16x32_bf16 v[136:139], v[228:231], v[76:79], v[24:27]
	v_mfma_f32_16x16x32_bf16 v[172:175], v[108:111], v[200:203], v[12:15]
	v_mfma_f32_16x16x32_bf16 v[176:179], v[228:231], v[200:203], v[8:11]
	s_setprio 0
	s_barrier
	s_nop 0
	ds_read_b128 v[8:11], v169
	ds_read_b128 v[12:15], v169 offset:1024
	ds_read_b128 v[196:199], v169 offset:2048
	ds_read_b128 v[200:203], v169 offset:3072
	ds_read_b128 v[24:27], v164 offset:32768
	ds_read_b128 v[28:31], v164 offset:33792
	ds_read_b128 v[40:43], v165 offset:32768
	ds_read_b128 v[44:47], v165 offset:33792
	ds_read_b128 v[204:207], v166 offset:32768
	ds_read_b128 v[208:211], v166 offset:33792
	ds_read_b128 v[228:231], v167 offset:32768
	ds_read_b128 v[240:243], v167 offset:33792
	s_waitcnt vmcnt(2)
	s_barrier
	s_waitcnt lgkmcnt(0)
	s_setprio 1
	s_waitcnt lgkmcnt(7)
	v_mfma_f32_16x16x32_bf16 v[68:71], v[8:11], v[24:27], v[124:127]
	s_waitcnt lgkmcnt(6)
	v_mfma_f32_16x16x32_bf16 v[124:127], v[12:15], v[28:31], v[68:71]
	v_mfma_f32_16x16x32_bf16 v[68:71], v[196:199], v[24:27], v[120:123]
	v_mfma_f32_16x16x32_bf16 v[116:119], v[200:203], v[28:31], v[68:71]
	s_waitcnt lgkmcnt(5)
	v_mfma_f32_16x16x32_bf16 v[68:71], v[8:11], v[40:43], v[216:219]
	s_waitcnt lgkmcnt(4)
	v_mfma_f32_16x16x32_bf16 v[108:111], v[12:15], v[44:47], v[68:71]
	v_mfma_f32_16x16x32_bf16 v[68:71], v[196:199], v[40:43], v[112:115]
	v_mfma_f32_16x16x32_bf16 v[100:103], v[200:203], v[44:47], v[68:71]
	s_waitcnt lgkmcnt(3)
	v_mfma_f32_16x16x32_bf16 v[68:71], v[8:11], v[204:207], v[220:223]
	s_waitcnt lgkmcnt(2)
	v_mfma_f32_16x16x32_bf16 v[92:95], v[12:15], v[208:211], v[68:71]
	v_mfma_f32_16x16x32_bf16 v[68:71], v[196:199], v[204:207], v[104:107]
	v_mfma_f32_16x16x32_bf16 v[84:87], v[200:203], v[208:211], v[68:71]
	s_waitcnt lgkmcnt(1)
	v_mfma_f32_16x16x32_bf16 v[68:71], v[8:11], v[228:231], v[224:227]
	s_waitcnt lgkmcnt(0)
	v_mfma_f32_16x16x32_bf16 v[76:79], v[12:15], v[240:243], v[68:71]
	v_mfma_f32_16x16x32_bf16 v[68:71], v[196:199], v[228:231], v[96:99]
	v_mfma_f32_16x16x32_bf16 v[68:71], v[200:203], v[240:243], v[68:71]
	s_setprio 0
	s_barrier
	ds_read_b128 v[216:219], v170
	ds_read_b128 v[220:223], v170 offset:1024
	ds_read_b128 v[224:227], v170 offset:2048
	ds_read_b128 v[244:247], v170 offset:3072
	s_waitcnt vmcnt(0)
	s_barrier
	s_waitcnt lgkmcnt(0)
	s_setprio 1
	s_waitcnt lgkmcnt(3)
	v_mfma_f32_16x16x32_bf16 v[96:99], v[216:219], v[24:27], v[232:235]
	s_waitcnt lgkmcnt(1)
	v_mfma_f32_16x16x32_bf16 v[24:27], v[224:227], v[24:27], v[88:91]
	s_waitcnt lgkmcnt(0)
	v_mfma_f32_16x16x32_bf16 v[112:115], v[244:247], v[28:31], v[24:27]
	v_mfma_f32_16x16x32_bf16 v[24:27], v[216:219], v[40:43], v[180:183]
	v_mfma_f32_16x16x32_bf16 v[104:107], v[220:223], v[44:47], v[24:27]
	v_mfma_f32_16x16x32_bf16 v[24:27], v[224:227], v[40:43], v[80:83]
	v_mfma_f32_16x16x32_bf16 v[120:123], v[220:223], v[28:31], v[96:99]
	v_mfma_f32_16x16x32_bf16 v[96:99], v[244:247], v[44:47], v[24:27]
	v_mfma_f32_16x16x32_bf16 v[24:27], v[216:219], v[204:207], v[184:187]
	v_mfma_f32_16x16x32_bf16 v[88:91], v[220:223], v[208:211], v[24:27]
	v_mfma_f32_16x16x32_bf16 v[24:27], v[224:227], v[204:207], v[72:75]
	v_mfma_f32_16x16x32_bf16 v[80:83], v[244:247], v[208:211], v[24:27]
	v_mfma_f32_16x16x32_bf16 v[24:27], v[216:219], v[228:231], v[188:191]
	v_mfma_f32_16x16x32_bf16 v[72:75], v[220:223], v[240:243], v[24:27]
	v_mfma_f32_16x16x32_bf16 v[24:27], v[224:227], v[228:231], v[64:67]
	v_mfma_f32_16x16x32_bf16 v[64:67], v[244:247], v[240:243], v[24:27]
	s_setprio 0
	s_barrier
; #define WAIT_L(n) asm volatile("s_waitcnt lgkmcnt(" #n ")" ::: "memory")
; #define BAR __builtin_amdgcn_s_barrier()
; #define SCHED __builtin_amdgcn_sched_barrier(0)
; template <int EPI>
; __device__ void gemm8_phase(const Params& p, const u16* __restrict__ A, const u16* __restrict__ Bt, const int K, const int nN,
;                             unsigned char* smem, const int rep) {
;     ...
;       LDA(At, 1, 1); BAR; WAIT_L(0); MMA(1, 0, At, B0); MMA(1, 1, At, B1); BAR; SCHED;
;     }
;     if (wr == 0) BAR;
;     ...
; #pragma unroll
;           for (int j = 0; j < 4; ++j) {
;             __builtin_amdgcn_sched_barrier(0);
;             const int row = brow + ai * HALF + wr * 64 + m * 16 + fq * 4 + j;
;             u16* proj = projb + (size_t)row * PROJ_LD;
;             float* cvo = nullptr;
;             if (EPI == 2 && bcol >= 2048) {
;               if (row < NPROMPT) {
;                 const int t = row & 2047;
;                 if (t >= 2045) cvo = p.out + OUT_CONVP + ((size_t)(row >> 11) * 3 + (t - 2045)) * 4096;
;               } else {
;                 const int rs = row - NPROMPT, t = rs & 7;
;                 if (t >= 5) cvo = p.out + OUT_CONVS + ((size_t)(rs >> 3) * 3 + (t - 5)) * 4096;
;               }
;             }
; #pragma unroll
;             for (int bj = 0; bj < 2; ++bj)
; #pragma unroll
;               for (int n = 0; n < 2; ++n) {
;                 const int col = bcol + bj * HALF + wc * 32 + n * 16 + fr;
;                 const float a = acc[ai][bj][m][n][j];
;                 proj[col] = f2bf(a);
;                 if (EPI == 2 && cvo) cvo[col - 2048] = a;
;               }
	ds_read_b128 v[180:183], v164 offset:49152
	ds_read_b128 v[184:187], v164 offset:50176
	ds_read_b128 v[188:191], v165 offset:49152
	ds_read_b128 v[204:207], v165 offset:50176
	ds_read_b128 v[208:211], v166 offset:49152
	ds_read_b128 v[228:231], v166 offset:50176
	ds_read_b128 v[232:235], v167 offset:49152
	ds_read_b128 v[240:243], v167 offset:50176
	s_barrier
	s_waitcnt lgkmcnt(0)
	s_setprio 1
	s_waitcnt lgkmcnt(7)
	v_mfma_f32_16x16x32_bf16 v[24:27], v[8:11], v[180:183], v[60:63]
	s_waitcnt lgkmcnt(6)
	v_mfma_f32_16x16x32_bf16 v[60:63], v[12:15], v[184:187], v[24:27]
	v_mfma_f32_16x16x32_bf16 v[24:27], v[196:199], v[180:183], v[56:59]
	v_mfma_f32_16x16x32_bf16 v[56:59], v[200:203], v[184:187], v[24:27]
	s_waitcnt lgkmcnt(5)
	v_mfma_f32_16x16x32_bf16 v[24:27], v[8:11], v[188:191], v[52:55]
	s_waitcnt lgkmcnt(4)
	v_mfma_f32_16x16x32_bf16 v[44:47], v[12:15], v[204:207], v[24:27]
	v_mfma_f32_16x16x32_bf16 v[24:27], v[196:199], v[188:191], v[48:51]
	v_mfma_f32_16x16x32_bf16 v[40:43], v[200:203], v[204:207], v[24:27]
	s_waitcnt lgkmcnt(3)
	v_mfma_f32_16x16x32_bf16 v[24:27], v[8:11], v[208:211], v[212:215]
	s_waitcnt lgkmcnt(1)
	v_mfma_f32_16x16x32_bf16 v[8:11], v[8:11], v[232:235], v[36:39]
	v_mfma_f32_16x16x32_bf16 v[28:31], v[12:15], v[228:231], v[24:27]
	v_mfma_f32_16x16x32_bf16 v[24:27], v[196:199], v[208:211], v[236:239]
	s_waitcnt lgkmcnt(0)
	v_mfma_f32_16x16x32_bf16 v[12:15], v[12:15], v[240:243], v[8:11]
	v_mfma_f32_16x16x32_bf16 v[8:11], v[196:199], v[232:235], v[32:35]
	v_mfma_f32_16x16x32_bf16 v[24:27], v[200:203], v[228:231], v[24:27]
	v_mfma_f32_16x16x32_bf16 v[8:11], v[200:203], v[240:243], v[8:11]
	s_setprio 0
	s_setprio 1
	v_mfma_f32_16x16x32_bf16 v[32:35], v[216:219], v[180:183], v[132:135]
	v_mfma_f32_16x16x32_bf16 v[52:55], v[220:223], v[184:187], v[32:35]
	v_mfma_f32_16x16x32_bf16 v[32:35], v[224:227], v[180:183], v[136:139]
	v_mfma_f32_16x16x32_bf16 v[16:19], v[224:227], v[188:191], v[16:19]
	v_mfma_f32_16x16x32_bf16 v[48:51], v[244:247], v[184:187], v[32:35]
	v_mfma_f32_16x16x32_bf16 v[20:23], v[216:219], v[188:191], v[20:23]
	v_mfma_f32_16x16x32_bf16 v[32:35], v[244:247], v[204:207], v[16:19]
	v_mfma_f32_16x16x32_bf16 v[16:19], v[216:219], v[208:211], v[172:175]
	v_mfma_f32_16x16x32_bf16 v[36:39], v[220:223], v[204:207], v[20:23]
	v_mfma_f32_16x16x32_bf16 v[20:23], v[220:223], v[228:231], v[16:19]
	v_mfma_f32_16x16x32_bf16 v[16:19], v[224:227], v[208:211], v[176:179]
	v_mfma_f32_16x16x32_bf16 v[4:7], v[216:219], v[232:235], v[4:7]
	v_mfma_f32_16x16x32_bf16 v[0:3], v[224:227], v[232:235], v[0:3]
	v_mfma_f32_16x16x32_bf16 v[16:19], v[244:247], v[228:231], v[16:19]
	v_mfma_f32_16x16x32_bf16 v[4:7], v[220:223], v[240:243], v[4:7]
	v_mfma_f32_16x16x32_bf16 v[0:3], v[244:247], v[240:243], v[0:3]
	s_setprio 0
	s_barrier
	s_andn2_b64 vcc, exec, s[22:23]
	s_cbranch_vccnz .LBB0_1064
	s_barrier
.LBB0_1064:
	v_readlane_b32 s5, v255, 6
	s_lshl_b32 s33, s1, 9
	s_lshl_b32 s30, s4, 8
	s_lshr_b32 s6, s5, 2
	s_and_b32 s5, s5, 3
	s_lshl_b32 s31, s6, 6
	v_and_b32_e32 v176, 15, v156
	v_lshrrev_b32_e32 v177, 4, v156
	v_add_u32_e32 v178, s31, v176
	v_mul_u32_u24_e32 v179, 0x210, v178
	s_lshl_b32 s7, s5, 6
	v_lshl_add_u32 v179, v177, 3, v179
	v_add_u32_e32 v179, s7, v179
	v_add_u32_e32 v180, 0x10800, v179
	s_cmp_lt_u32 s1, 8
	s_cbranch_scc1 .Lg5_plain
	s_lshl_b32 s0, s33, 1
	s_add_i32 s0, s0, 0xffffe000
	s_lshl_b32 s7, s5, 7
	s_add_i32 s0, s0, s7
	s_cmp_ge_u32 s4, 64
	s_cbranch_scc1 .Lg5_conv_sample
	s_and_b32 s7, s4, 7
	s_cmp_eq_u32 s7, 7
	s_cbranch_scc0 .Lg5_plain
	s_cmp_eq_u32 s6, 1
	s_cbranch_scc1 .Lg5_conv_prompt
.Lg5_plain:
	v_cvt_pk_bf16_f32 v124, v124, v125
	v_cvt_pk_bf16_f32 v125, v126, v127
	ds_write_b64 v179, v[124:125]
	v_cvt_pk_bf16_f32 v116, v116, v117
	v_cvt_pk_bf16_f32 v117, v118, v119
	ds_write_b64 v179, v[116:117] offset:32
	v_cvt_pk_bf16_f32 v120, v120, v121
	v_cvt_pk_bf16_f32 v121, v122, v123
	ds_write_b64 v179, v[120:121] offset:256
	v_cvt_pk_bf16_f32 v112, v112, v113
	v_cvt_pk_bf16_f32 v113, v114, v115
	ds_write_b64 v179, v[112:113] offset:288
	v_cvt_pk_bf16_f32 v108, v108, v109
	v_cvt_pk_bf16_f32 v109, v110, v111
	ds_write_b64 v179, v[108:109] offset:8448
	v_cvt_pk_bf16_f32 v100, v100, v101
	v_cvt_pk_bf16_f32 v101, v102, v103
	ds_write_b64 v179, v[100:101] offset:8480
	v_cvt_pk_bf16_f32 v104, v104, v105
	v_cvt_pk_bf16_f32 v105, v106, v107
	ds_write_b64 v179, v[104:105] offset:8704
	v_cvt_pk_bf16_f32 v96, v96, v97
	v_cvt_pk_bf16_f32 v97, v98, v99
	ds_write_b64 v179, v[96:97] offset:8736
	v_cvt_pk_bf16_f32 v92, v92, v93
	v_cvt_pk_bf16_f32 v93, v94, v95
	ds_write_b64 v179, v[92:93] offset:16896
	v_cvt_pk_bf16_f32 v84, v84, v85
	v_cvt_pk_bf16_f32 v85, v86, v87
	ds_write_b64 v179, v[84:85] offset:16928
	v_cvt_pk_bf16_f32 v88, v88, v89
	v_cvt_pk_bf16_f32 v89, v90, v91
	ds_write_b64 v179, v[88:89] offset:17152
	v_cvt_pk_bf16_f32 v80, v80, v81
	v_cvt_pk_bf16_f32 v81, v82, v83
	ds_write_b64 v179, v[80:81] offset:17184
	v_cvt_pk_bf16_f32 v76, v76, v77
	v_cvt_pk_bf16_f32 v77, v78, v79
	ds_write_b64 v179, v[76:77] offset:25344
	v_cvt_pk_bf16_f32 v68, v68, v69
	v_cvt_pk_bf16_f32 v69, v70, v71
	ds_write_b64 v179, v[68:69] offset:25376
	v_cvt_pk_bf16_f32 v72, v72, v73
	v_cvt_pk_bf16_f32 v73, v74, v75
	ds_write_b64 v179, v[72:73] offset:25600
	v_cvt_pk_bf16_f32 v64, v64, v65
	v_cvt_pk_bf16_f32 v65, v66, v67
	ds_write_b64 v179, v[64:65] offset:25632
	v_cvt_pk_bf16_f32 v60, v60, v61
	v_cvt_pk_bf16_f32 v61, v62, v63
	ds_write_b64 v180, v[60:61]
	v_cvt_pk_bf16_f32 v56, v56, v57
	v_cvt_pk_bf16_f32 v57, v58, v59
	ds_write_b64 v180, v[56:57] offset:32
	v_cvt_pk_bf16_f32 v52, v52, v53
	v_cvt_pk_bf16_f32 v53, v54, v55
	ds_write_b64 v180, v[52:53] offset:256
; template <int EPI>
; __device__ void gemm8_phase(const Params& p, const u16* __restrict__ A, const u16* __restrict__ Bt, const int K, const int nN,
;                             unsigned char* smem, const int rep) {
;     ...
;             float* cvo = nullptr;
;             if (EPI == 2 && bcol >= 2048) {
;               if (row < NPROMPT) {
;                 const int t = row & 2047;
;                 if (t >= 2045) cvo = p.out + OUT_CONVP + ((size_t)(row >> 11) * 3 + (t - 2045)) * 4096;
;               } else {
;                 const int rs = row - NPROMPT, t = rs & 7;
;                 if (t >= 5) cvo = p.out + OUT_CONVS + ((size_t)(rs >> 3) * 3 + (t - 5)) * 4096;
;               }
;             }
; #pragma unroll
;             for (int bj = 0; bj < 2; ++bj)
; #pragma unroll
;               for (int n = 0; n < 2; ++n) {
;                 const int col = bcol + bj * HALF + wc * 32 + n * 16 + fr;
;                 const float a = acc[ai][bj][m][n][j];
;                 proj[col] = f2bf(a);
;                 if (EPI == 2 && cvo) cvo[col - 2048] = a;
;               }
	v_cvt_pk_bf16_f32 v48, v48, v49
	v_cvt_pk_bf16_f32 v49, v50, v51
	ds_write_b64 v180, v[48:49] offset:288
	v_cvt_pk_bf16_f32 v44, v44, v45
	v_cvt_pk_bf16_f32 v45, v46, v47
	ds_write_b64 v180, v[44:45] offset:8448
	v_cvt_pk_bf16_f32 v40, v40, v41
	v_cvt_pk_bf16_f32 v41, v42, v43
	ds_write_b64 v180, v[40:41] offset:8480
	v_cvt_pk_bf16_f32 v36, v36, v37
	v_cvt_pk_bf16_f32 v37, v38, v39
	ds_write_b64 v180, v[36:37] offset:8704
	v_cvt_pk_bf16_f32 v32, v32, v33
	v_cvt_pk_bf16_f32 v33, v34, v35
	ds_write_b64 v180, v[32:33] offset:8736
	v_cvt_pk_bf16_f32 v28, v28, v29
	v_cvt_pk_bf16_f32 v29, v30, v31
	ds_write_b64 v180, v[28:29] offset:16896
	v_cvt_pk_bf16_f32 v24, v24, v25
	v_cvt_pk_bf16_f32 v25, v26, v27
	ds_write_b64 v180, v[24:25] offset:16928
	v_cvt_pk_bf16_f32 v20, v20, v21
	v_cvt_pk_bf16_f32 v21, v22, v23
	ds_write_b64 v180, v[20:21] offset:17152
	v_cvt_pk_bf16_f32 v16, v16, v17
	v_cvt_pk_bf16_f32 v17, v18, v19
	ds_write_b64 v180, v[16:17] offset:17184
	v_cvt_pk_bf16_f32 v12, v12, v13
	v_cvt_pk_bf16_f32 v13, v14, v15
	ds_write_b64 v180, v[12:13] offset:25344
	v_cvt_pk_bf16_f32 v8, v8, v9
	v_cvt_pk_bf16_f32 v9, v10, v11
	ds_write_b64 v180, v[8:9] offset:25376
	v_cvt_pk_bf16_f32 v4, v4, v5
	v_cvt_pk_bf16_f32 v5, v6, v7
	ds_write_b64 v180, v[4:5] offset:25600
	v_cvt_pk_bf16_f32 v0, v0, v1
	v_cvt_pk_bf16_f32 v1, v2, v3
	ds_write_b64 v180, v[0:1] offset:25632
	s_branch .Lg5_readback
.Lg5_conv_sample:
	s_add_i32 s7, s30, s31
	v_add_u32_e32 v181, s7, v176
	v_subrev_u32_e32 v182, 0x4000, v181
	v_lshrrev_b32_e32 v183, 3, v182
	v_and_b32_e32 v182, 7, v182
	v_mad_u32_u24 v183, v183, 3, v182
	v_cmp_lt_u32_e32 vcc, 4, v182
	v_add_u32_e32 v183, -5, v183
	v_lshlrev_b32_e32 v183, 14, v183
	v_lshl_add_u32 v183, v177, 4, v183
	v_add_u32_e32 v183, s0, v183
	s_mov_b64 s[36:37], vcc
	s_and_saveexec_b64 s[34:35], s[36:37]
	global_store_dwordx4 v183, v[124:127], s[26:27]
	global_store_dwordx4 v183, v[116:119], s[26:27] offset:64
	global_store_dwordx4 v183, v[120:123], s[26:27] offset:512
	global_store_dwordx4 v183, v[112:115], s[26:27] offset:576
	s_nop 1
	s_mov_b64 exec, s[34:35]
	s_nop 0
	v_cvt_pk_bf16_f32 v124, v124, v125
	v_cvt_pk_bf16_f32 v125, v126, v127
	ds_write_b64 v179, v[124:125]
	v_cvt_pk_bf16_f32 v116, v116, v117
	v_cvt_pk_bf16_f32 v117, v118, v119
	ds_write_b64 v179, v[116:117] offset:32
	v_cvt_pk_bf16_f32 v120, v120, v121
	v_cvt_pk_bf16_f32 v121, v122, v123
	ds_write_b64 v179, v[120:121] offset:256
	v_cvt_pk_bf16_f32 v112, v112, v113
	v_cvt_pk_bf16_f32 v113, v114, v115
	ds_write_b64 v179, v[112:113] offset:288
	v_add_u32_e32 v184, 0x18000, v183
	s_and_saveexec_b64 s[34:35], s[36:37]
	global_store_dwordx4 v184, v[108:111], s[26:27]
	global_store_dwordx4 v184, v[100:103], s[26:27] offset:64
	global_store_dwordx4 v184, v[104:107], s[26:27] offset:512
	global_store_dwordx4 v184, v[96:99], s[26:27] offset:576
	s_nop 1
	s_mov_b64 exec, s[34:35]
	s_nop 0
	v_cvt_pk_bf16_f32 v108, v108, v109
	v_cvt_pk_bf16_f32 v109, v110, v111
	ds_write_b64 v179, v[108:109] offset:8448
	v_cvt_pk_bf16_f32 v100, v100, v101
	v_cvt_pk_bf16_f32 v101, v102, v103
	ds_write_b64 v179, v[100:101] offset:8480
	v_cvt_pk_bf16_f32 v104, v104, v105
	v_cvt_pk_bf16_f32 v105, v106, v107
	ds_write_b64 v179, v[104:105] offset:8704
	v_cvt_pk_bf16_f32 v96, v96, v97
	v_cvt_pk_bf16_f32 v97, v98, v99
	ds_write_b64 v179, v[96:97] offset:8736
	v_add_u32_e32 v184, 0x30000, v183
	s_and_saveexec_b64 s[34:35], s[36:37]
	global_store_dwordx4 v184, v[92:95], s[26:27]
	global_store_dwordx4 v184, v[84:87], s[26:27] offset:64
	global_store_dwordx4 v184, v[88:91], s[26:27] offset:512
	global_store_dwordx4 v184, v[80:83], s[26:27] offset:576
	s_nop 1
	s_mov_b64 exec, s[34:35]
	s_nop 0
	v_cvt_pk_bf16_f32 v92, v92, v93
	v_cvt_pk_bf16_f32 v93, v94, v95
	ds_write_b64 v179, v[92:93] offset:16896
	v_cvt_pk_bf16_f32 v84, v84, v85
	v_cvt_pk_bf16_f32 v85, v86, v87
	ds_write_b64 v179, v[84:85] offset:16928
	v_cvt_pk_bf16_f32 v88, v88, v89
	v_cvt_pk_bf16_f32 v89, v90, v91
	ds_write_b64 v179, v[88:89] offset:17152
	v_cvt_pk_bf16_f32 v80, v80, v81
	v_cvt_pk_bf16_f32 v81, v82, v83
	ds_write_b64 v179, v[80:81] offset:17184
	v_add_u32_e32 v184, 0x48000, v183
	s_and_saveexec_b64 s[34:35], s[36:37]
	global_store_dwordx4 v184, v[76:79], s[26:27]
	global_store_dwordx4 v184, v[68:71], s[26:27] offset:64
	global_store_dwordx4 v184, v[72:75], s[26:27] offset:512
	global_store_dwordx4 v184, v[64:67], s[26:27] offset:576
	s_nop 1
	s_mov_b64 exec, s[34:35]
	s_nop 0
	v_cvt_pk_bf16_f32 v76, v76, v77
	v_cvt_pk_bf16_f32 v77, v78, v79
	ds_write_b64 v179, v[76:77] offset:25344
	v_cvt_pk_bf16_f32 v68, v68, v69
	v_cvt_pk_bf16_f32 v69, v70, v71
	ds_write_b64 v179, v[68:69] offset:25376
	v_cvt_pk_bf16_f32 v72, v72, v73
	v_cvt_pk_bf16_f32 v73, v74, v75
	ds_write_b64 v179, v[72:73] offset:25600
	v_cvt_pk_bf16_f32 v64, v64, v65
	v_cvt_pk_bf16_f32 v65, v66, v67
	ds_write_b64 v179, v[64:65] offset:25632
	v_add_u32_e32 v184, 0xc0000, v183
	s_and_saveexec_b64 s[34:35], s[36:37]
	global_store_dwordx4 v184, v[60:63], s[26:27]
	global_store_dwordx4 v184, v[56:59], s[26:27] offset:64
	global_store_dwordx4 v184, v[52:55], s[26:27] offset:512
	global_store_dwordx4 v184, v[48:51], s[26:27] offset:576
	s_nop 1
	s_mov_b64 exec, s[34:35]
	s_nop 0
	v_cvt_pk_bf16_f32 v60, v60, v61
	v_cvt_pk_bf16_f32 v61, v62, v63
	ds_write_b64 v180, v[60:61]
	v_cvt_pk_bf16_f32 v56, v56, v57
	v_cvt_pk_bf16_f32 v57, v58, v59
	ds_write_b64 v180, v[56:57] offset:32
	v_cvt_pk_bf16_f32 v52, v52, v53
	v_cvt_pk_bf16_f32 v53, v54, v55
	ds_write_b64 v180, v[52:53] offset:256
	v_cvt_pk_bf16_f32 v48, v48, v49
	v_cvt_pk_bf16_f32 v49, v50, v51
	ds_write_b64 v180, v[48:49] offset:288
; template <int EPI>
; __device__ void gemm8_phase(const Params& p, const u16* __restrict__ A, const u16* __restrict__ Bt, const int K, const int nN,
;                             unsigned char* smem, const int rep) {
;     ...
;             float* cvo = nullptr;
;             if (EPI == 2 && bcol >= 2048) {
;               if (row < NPROMPT) {
;                 const int t = row & 2047;
;                 if (t >= 2045) cvo = p.out + OUT_CONVP + ((size_t)(row >> 11) * 3 + (t - 2045)) * 4096;
;               } else {
;                 const int rs = row - NPROMPT, t = rs & 7;
;                 if (t >= 5) cvo = p.out + OUT_CONVS + ((size_t)(rs >> 3) * 3 + (t - 5)) * 4096;
;               }
;             }
; #pragma unroll
;             for (int bj = 0; bj < 2; ++bj)
; #pragma unroll
;               for (int n = 0; n < 2; ++n) {
;                 const int col = bcol + bj * HALF + wc * 32 + n * 16 + fr;
;                 const float a = acc[ai][bj][m][n][j];
;                 proj[col] = f2bf(a);
;                 if (EPI == 2 && cvo) cvo[col - 2048] = a;
;               }
	v_add_u32_e32 v184, 0xd8000, v183
	s_and_saveexec_b64 s[34:35], s[36:37]
	global_store_dwordx4 v184, v[44:47], s[26:27]
	global_store_dwordx4 v184, v[40:43], s[26:27] offset:64
	global_store_dwordx4 v184, v[36:39], s[26:27] offset:512
	global_store_dwordx4 v184, v[32:35], s[26:27] offset:576
	s_nop 1
	s_mov_b64 exec, s[34:35]
	s_nop 0
	v_cvt_pk_bf16_f32 v44, v44, v45
	v_cvt_pk_bf16_f32 v45, v46, v47
	ds_write_b64 v180, v[44:45] offset:8448
	v_cvt_pk_bf16_f32 v40, v40, v41
	v_cvt_pk_bf16_f32 v41, v42, v43
	ds_write_b64 v180, v[40:41] offset:8480
	v_cvt_pk_bf16_f32 v36, v36, v37
	v_cvt_pk_bf16_f32 v37, v38, v39
	ds_write_b64 v180, v[36:37] offset:8704
	v_cvt_pk_bf16_f32 v32, v32, v33
	v_cvt_pk_bf16_f32 v33, v34, v35
	ds_write_b64 v180, v[32:33] offset:8736
	v_add_u32_e32 v184, 0xf0000, v183
	s_and_saveexec_b64 s[34:35], s[36:37]
	global_store_dwordx4 v184, v[28:31], s[26:27]
	global_store_dwordx4 v184, v[24:27], s[26:27] offset:64
	global_store_dwordx4 v184, v[20:23], s[26:27] offset:512
	global_store_dwordx4 v184, v[16:19], s[26:27] offset:576
	s_nop 1
	s_mov_b64 exec, s[34:35]
	s_nop 0
	v_cvt_pk_bf16_f32 v28, v28, v29
	v_cvt_pk_bf16_f32 v29, v30, v31
	ds_write_b64 v180, v[28:29] offset:16896
	v_cvt_pk_bf16_f32 v24, v24, v25
	v_cvt_pk_bf16_f32 v25, v26, v27
	ds_write_b64 v180, v[24:25] offset:16928
	v_cvt_pk_bf16_f32 v20, v20, v21
	v_cvt_pk_bf16_f32 v21, v22, v23
	ds_write_b64 v180, v[20:21] offset:17152
	v_cvt_pk_bf16_f32 v16, v16, v17
	v_cvt_pk_bf16_f32 v17, v18, v19
	ds_write_b64 v180, v[16:17] offset:17184
	v_add_u32_e32 v184, 0x108000, v183
	s_and_saveexec_b64 s[34:35], s[36:37]
	global_store_dwordx4 v184, v[12:15], s[26:27]
	global_store_dwordx4 v184, v[8:11], s[26:27] offset:64
	global_store_dwordx4 v184, v[4:7], s[26:27] offset:512
	global_store_dwordx4 v184, v[0:3], s[26:27] offset:576
	s_nop 1
	s_mov_b64 exec, s[34:35]
	s_nop 0
	v_cvt_pk_bf16_f32 v12, v12, v13
	v_cvt_pk_bf16_f32 v13, v14, v15
	ds_write_b64 v180, v[12:13] offset:25344
	v_cvt_pk_bf16_f32 v8, v8, v9
	v_cvt_pk_bf16_f32 v9, v10, v11
	ds_write_b64 v180, v[8:9] offset:25376
	v_cvt_pk_bf16_f32 v4, v4, v5
	v_cvt_pk_bf16_f32 v5, v6, v7
	ds_write_b64 v180, v[4:5] offset:25600
	v_cvt_pk_bf16_f32 v0, v0, v1
	v_cvt_pk_bf16_f32 v1, v2, v3
	ds_write_b64 v180, v[0:1] offset:25632
	s_branch .Lg5_readback
.Lg5_conv_prompt:
	s_lshr_b32 s7, s4, 3
	s_mul_i32 s7, s7, 3
	s_sub_i32 s7, s7, 13
	v_add_u32_e32 v183, s7, v176
	v_cmp_lt_u32_e32 vcc, 12, v176
	v_lshlrev_b32_e32 v183, 14, v183
	v_lshl_add_u32 v183, v177, 4, v183
	v_add_u32_e32 v183, s0, v183
	s_mov_b64 s[36:37], vcc
	v_cvt_pk_bf16_f32 v124, v124, v125
	v_cvt_pk_bf16_f32 v125, v126, v127
	ds_write_b64 v179, v[124:125]
	v_cvt_pk_bf16_f32 v116, v116, v117
	v_cvt_pk_bf16_f32 v117, v118, v119
	ds_write_b64 v179, v[116:117] offset:32
	v_cvt_pk_bf16_f32 v120, v120, v121
	v_cvt_pk_bf16_f32 v121, v122, v123
	ds_write_b64 v179, v[120:121] offset:256
	v_cvt_pk_bf16_f32 v112, v112, v113
	v_cvt_pk_bf16_f32 v113, v114, v115
	ds_write_b64 v179, v[112:113] offset:288
	v_cvt_pk_bf16_f32 v108, v108, v109
	v_cvt_pk_bf16_f32 v109, v110, v111
	ds_write_b64 v179, v[108:109] offset:8448
	v_cvt_pk_bf16_f32 v100, v100, v101
	v_cvt_pk_bf16_f32 v101, v102, v103
	ds_write_b64 v179, v[100:101] offset:8480
	v_cvt_pk_bf16_f32 v104, v104, v105
	v_cvt_pk_bf16_f32 v105, v106, v107
	ds_write_b64 v179, v[104:105] offset:8704
	v_cvt_pk_bf16_f32 v96, v96, v97
	v_cvt_pk_bf16_f32 v97, v98, v99
	ds_write_b64 v179, v[96:97] offset:8736
	v_cvt_pk_bf16_f32 v92, v92, v93
	v_cvt_pk_bf16_f32 v93, v94, v95
	ds_write_b64 v179, v[92:93] offset:16896
	v_cvt_pk_bf16_f32 v84, v84, v85
	v_cvt_pk_bf16_f32 v85, v86, v87
	ds_write_b64 v179, v[84:85] offset:16928
	v_cvt_pk_bf16_f32 v88, v88, v89
	v_cvt_pk_bf16_f32 v89, v90, v91
	ds_write_b64 v179, v[88:89] offset:17152
	v_cvt_pk_bf16_f32 v80, v80, v81
	v_cvt_pk_bf16_f32 v81, v82, v83
	ds_write_b64 v179, v[80:81] offset:17184
	v_cvt_pk_bf16_f32 v76, v76, v77
	v_cvt_pk_bf16_f32 v77, v78, v79
	ds_write_b64 v179, v[76:77] offset:25344
	v_cvt_pk_bf16_f32 v68, v68, v69
	v_cvt_pk_bf16_f32 v69, v70, v71
	ds_write_b64 v179, v[68:69] offset:25376
	v_cvt_pk_bf16_f32 v72, v72, v73
	v_cvt_pk_bf16_f32 v73, v74, v75
	ds_write_b64 v179, v[72:73] offset:25600
	v_cvt_pk_bf16_f32 v64, v64, v65
	v_cvt_pk_bf16_f32 v65, v66, v67
	ds_write_b64 v179, v[64:65] offset:25632
	v_cvt_pk_bf16_f32 v60, v60, v61
	v_cvt_pk_bf16_f32 v61, v62, v63
	ds_write_b64 v180, v[60:61]
	v_cvt_pk_bf16_f32 v56, v56, v57
	v_cvt_pk_bf16_f32 v57, v58, v59
	ds_write_b64 v180, v[56:57] offset:32
	v_cvt_pk_bf16_f32 v52, v52, v53
	v_cvt_pk_bf16_f32 v53, v54, v55
	ds_write_b64 v180, v[52:53] offset:256
	v_cvt_pk_bf16_f32 v48, v48, v49
	v_cvt_pk_bf16_f32 v49, v50, v51
	ds_write_b64 v180, v[48:49] offset:288
	v_cvt_pk_bf16_f32 v44, v44, v45
	v_cvt_pk_bf16_f32 v45, v46, v47
	ds_write_b64 v180, v[44:45] offset:8448
	v_cvt_pk_bf16_f32 v40, v40, v41
	v_cvt_pk_bf16_f32 v41, v42, v43
	ds_write_b64 v180, v[40:41] offset:8480
	v_cvt_pk_bf16_f32 v36, v36, v37
	v_cvt_pk_bf16_f32 v37, v38, v39
	ds_write_b64 v180, v[36:37] offset:8704
	v_cvt_pk_bf16_f32 v32, v32, v33
	v_cvt_pk_bf16_f32 v33, v34, v35
	ds_write_b64 v180, v[32:33] offset:8736
	v_cvt_pk_bf16_f32 v28, v28, v29
	v_cvt_pk_bf16_f32 v29, v30, v31
	ds_write_b64 v180, v[28:29] offset:16896
	v_cvt_pk_bf16_f32 v24, v24, v25
	v_cvt_pk_bf16_f32 v25, v26, v27
	ds_write_b64 v180, v[24:25] offset:16928
	v_cvt_pk_bf16_f32 v20, v20, v21
	v_cvt_pk_bf16_f32 v21, v22, v23
	ds_write_b64 v180, v[20:21] offset:17152
	v_cvt_pk_bf16_f32 v16, v16, v17
	v_cvt_pk_bf16_f32 v17, v18, v19
	ds_write_b64 v180, v[16:17] offset:17184
	s_and_saveexec_b64 s[34:35], s[36:37]
	global_store_dwordx4 v183, v[12:15], s[28:29]
	global_store_dwordx4 v183, v[8:11], s[28:29] offset:64
	global_store_dwordx4 v183, v[4:7], s[28:29] offset:512
	global_store_dwordx4 v183, v[0:3], s[28:29] offset:576
	s_nop 1
	s_mov_b64 exec, s[34:35]
	s_nop 0
	v_cvt_pk_bf16_f32 v12, v12, v13
	v_cvt_pk_bf16_f32 v13, v14, v15
	ds_write_b64 v180, v[12:13] offset:25344
	v_cvt_pk_bf16_f32 v8, v8, v9
	v_cvt_pk_bf16_f32 v9, v10, v11
	ds_write_b64 v180, v[8:9] offset:25376
	v_cvt_pk_bf16_f32 v4, v4, v5
	v_cvt_pk_bf16_f32 v5, v6, v7
	ds_write_b64 v180, v[4:5] offset:25600
	v_cvt_pk_bf16_f32 v0, v0, v1
	v_cvt_pk_bf16_f32 v1, v2, v3
	ds_write_b64 v180, v[0:1] offset:25632
; template <int EPI>
; __device__ void gemm8_phase(const Params& p, const u16* __restrict__ A, const u16* __restrict__ Bt, const int K, const int nN,
;                             unsigned char* smem, const int rep) {
;     ...
; #pragma unroll
;           for (int j = 0; j < 4; ++j) {
;             __builtin_amdgcn_sched_barrier(0);
;             const int row = brow + ai * HALF + wr * 64 + m * 16 + fq * 4 + j;
;             u16* proj = projb + (size_t)row * PROJ_LD;
;             float* cvo = nullptr;
;             if (EPI == 2 && bcol >= 2048) {
;               if (row < NPROMPT) {
;                 const int t = row & 2047;
;                 if (t >= 2045) cvo = p.out + OUT_CONVP + ((size_t)(row >> 11) * 3 + (t - 2045)) * 4096;
;               } else {
;                 const int rs = row - NPROMPT, t = rs & 7;
;                 if (t >= 5) cvo = p.out + OUT_CONVS + ((size_t)(rs >> 3) * 3 + (t - 5)) * 4096;
;               }
;             }
; #pragma unroll
;             for (int bj = 0; bj < 2; ++bj)
; #pragma unroll
;               for (int n = 0; n < 2; ++n) {
;                 const int col = bcol + bj * HALF + wc * 32 + n * 16 + fr;
;                 const float a = acc[ai][bj][m][n][j];
;                 proj[col] = f2bf(a);
;                 if (EPI == 2 && cvo) cvo[col - 2048] = a;
;               }
.Lg5_readback:
	s_waitcnt lgkmcnt(0)
	s_barrier
	v_readlane_b32 s7, v255, 6
	v_lshrrev_b32_e32 v178, 5, v156
	v_and_b32_e32 v176, 31, v156
	s_lshl_b32 s7, s7, 5
	v_add_u32_e32 v178, s7, v178
	v_lshlrev_b32_e32 v176, 4, v176
	v_add_u32_e32 v177, s30, v178
	v_mul_u32_u24_e32 v177, 0x3080, v177
	v_mul_u32_u24_e32 v178, 0x210, v178
	v_add3_u32 v177, v177, v176, s33
	v_add_u32_e32 v176, v178, v176
	ds_read_b128 v[0:3], v176
	ds_read_b128 v[4:7], v176 offset:1056
	ds_read_b128 v[8:11], v176 offset:2112
	ds_read_b128 v[12:15], v176 offset:3168
	ds_read_b128 v[16:19], v176 offset:4224
	ds_read_b128 v[20:23], v176 offset:5280
	ds_read_b128 v[24:27], v176 offset:6336
	ds_read_b128 v[28:31], v176 offset:7392
	ds_read_b128 v[32:35], v176 offset:8448
	ds_read_b128 v[36:39], v176 offset:9504
	ds_read_b128 v[40:43], v176 offset:10560
	ds_read_b128 v[44:47], v176 offset:11616
	ds_read_b128 v[48:51], v176 offset:12672
	ds_read_b128 v[52:55], v176 offset:13728
	ds_read_b128 v[56:59], v176 offset:14784
	ds_read_b128 v[60:63], v176 offset:15840
	s_waitcnt lgkmcnt(15)
	global_store_dwordx4 v177, v[0:3], s[24:25]
	v_add_u32_e32 v177, 0x6100, v177
	s_waitcnt lgkmcnt(14)
	global_store_dwordx4 v177, v[4:7], s[24:25]
	v_add_u32_e32 v177, 0x6100, v177
	s_waitcnt lgkmcnt(13)
	global_store_dwordx4 v177, v[8:11], s[24:25]
	v_add_u32_e32 v177, 0x6100, v177
	s_waitcnt lgkmcnt(12)
	global_store_dwordx4 v177, v[12:15], s[24:25]
	v_add_u32_e32 v177, 0x6100, v177
	s_waitcnt lgkmcnt(11)
	global_store_dwordx4 v177, v[16:19], s[24:25]
	v_add_u32_e32 v177, 0x6100, v177
	s_waitcnt lgkmcnt(10)
	global_store_dwordx4 v177, v[20:23], s[24:25]
	v_add_u32_e32 v177, 0x6100, v177
	s_waitcnt lgkmcnt(9)
	global_store_dwordx4 v177, v[24:27], s[24:25]
	v_add_u32_e32 v177, 0x6100, v177
	s_waitcnt lgkmcnt(8)
	global_store_dwordx4 v177, v[28:31], s[24:25]
	v_add_u32_e32 v177, 0x6100, v177
	s_waitcnt lgkmcnt(7)
	global_store_dwordx4 v177, v[32:35], s[24:25]
	v_add_u32_e32 v177, 0x6100, v177
	s_waitcnt lgkmcnt(6)
	global_store_dwordx4 v177, v[36:39], s[24:25]
	v_add_u32_e32 v177, 0x6100, v177
	s_waitcnt lgkmcnt(5)
	global_store_dwordx4 v177, v[40:43], s[24:25]
	v_add_u32_e32 v177, 0x6100, v177
	s_waitcnt lgkmcnt(4)
	global_store_dwordx4 v177, v[44:47], s[24:25]
	v_add_u32_e32 v177, 0x6100, v177
	s_waitcnt lgkmcnt(3)
	global_store_dwordx4 v177, v[48:51], s[24:25]
	v_add_u32_e32 v177, 0x6100, v177
	s_waitcnt lgkmcnt(2)
	global_store_dwordx4 v177, v[52:55], s[24:25]
	v_add_u32_e32 v177, 0x6100, v177
	s_waitcnt lgkmcnt(1)
	global_store_dwordx4 v177, v[56:59], s[24:25]
	v_add_u32_e32 v177, 0x6100, v177
	s_waitcnt lgkmcnt(0)
	global_store_dwordx4 v177, v[60:63], s[24:25]
	s_barrier
	s_add_i32 s47, s47, s96
	s_cmp_lt_i32 s47, s39
	s_cbranch_scc1 .LBB0_1058
	s_branch .LBB0_1220
